# GEMM loops: priority swapped (load segments prio 1, MFMA blocks prio 0) + SW sink lane table
# baseline (speedup 1.0000x reference)
; #define PG8_STAGE(bufoff, gbase, voff) do { _Pragma("unroll") for (int _i = 0; _i < 2; ++_i) \
;         __builtin_amdgcn_global_load_lds((const unsigned*)((const char*)(gbase) + (voff)[_i]), (PG8_LAS unsigned*)(lds + (bufoff) + ldsw + _i * 8192), 16, 0, 0); } while (0)
; #define PG8_LDA(dst, b, h) do { _Pragma("unroll") for (int m = 0; m < 4; ++m) _Pragma("unroll") for (int k = 0; k < 2; ++k) dst[m][k] = *(const PG8_LAS bf16x8*)(lds + PG8_SA(b, h) + aoff + m * 2048 + k * 1024); } while (0)
; #define PG8_LDB(dst, b, h) do { _Pragma("unroll") for (int n = 0; n < 2; ++n) _Pragma("unroll") for (int k = 0; k < 2; ++k) dst[n][k] = *(const PG8_LAS bf16x8*)(lds + PG8_SB(b, h) + boff + n * 2048 + k * 1024); } while (0)
; #define PG8_MMA(ai, bj, At, Bt) do { __builtin_amdgcn_s_setprio(1); _Pragma("unroll") for (int m = 0; m < 4; ++m) _Pragma("unroll") for (int n = 0; n < 2; ++n) _Pragma("unroll") for (int k = 0; k < 2; ++k) \
;         acc[ai][bj][m][n] = __builtin_amdgcn_mfma_f32_16x16x32_bf16(Bt[n][k], At[m][k], acc[ai][bj][m][n], 0, 0, 0); __builtin_amdgcn_s_setprio(0); } while (0)
; #define PG8_WAIT_V(n) asm volatile("s_waitcnt vmcnt(" #n ")" ::: "memory")
; #define PG8_WAIT_L(n) asm volatile("s_waitcnt lgkmcnt(" #n ")" ::: "memory")
; #define PG8_BAR __builtin_amdgcn_s_barrier()
; #define PG8_SCHED __builtin_amdgcn_sched_barrier(0)
; template <class Epi, class Sched, bool ALIGN_EPI = false, bool SP2 = false>
; __device__ __forceinline__ void gemm_phase(PG8_LAS unsigned char* lds, const Gemm g, const Sched& S, const Epi& E) {
;     ...
;             const bool last = (t == nt - 2);
;             const char* a1 = cA + (size_t)(t + 1) * kstep;
;             const char* a2 = last ? nA : cA + (size_t)(t + 2) * kstep; const char* b2 = last ? nB : cB + (size_t)(t + 2) * kstep;
;             const char* a3 = a2 + kstep; const char* b3 = b2 + kstep;
;             if (last && has_next) S.a_ready(nxt);
;             if constexpr (SP2) {
;             PG8_LDB(B0, 0, 0); PG8_LDB(B1, 0, 1); PG8_SCHED; PG8_LDA(At, 0, 0); PG8_STAGE(PG8_SA(1, 1), a1 + hstep, voffA);
;             PG8_WAIT_V(8); PG8_WAIT_L(0); PG8_BAR; PG8_MMA(0, 0, At, B0); PG8_MMA(0, 1, At, B1); PG8_BAR; PG8_SCHED;
;             PG8_LDA(At, 0, 1); PG8_STAGE(PG8_SB(0, 0), b2, voffB); PG8_STAGE(PG8_SB(0, 1), b2 + hstep, voffB); PG8_STAGE(PG8_SA(0, 0), a2, voffA);
.LBB0_237:
	s_add_u32 s44, s42, 0xfffc0080
	s_addc_u32 s45, s43, -1
	s_add_i32 s63, 0, 0x10000
	s_cmp_eq_u32 s62, 12
	s_cselect_b32 s47, s13, s45
	s_cselect_b32 s46, s19, s44
	v_add_u32_e32 v141, s63, v145
	s_cselect_b32 s45, s11, s61
	s_cselect_b32 s44, s41, s60
	s_add_i32 s66, 0, 0x14000
	ds_read_b128 v[150:153], v141
	ds_read_b128 v[170:173], v141 offset:1024
	ds_read_b128 v[174:177], v141 offset:2048
	ds_read_b128 v[178:181], v141 offset:3072
	v_add_u32_e32 v141, s66, v145
	ds_read_b128 v[182:185], v141
	ds_read_b128 v[186:189], v141 offset:1024
	ds_read_b128 v[190:193], v141 offset:2048
	ds_read_b128 v[194:197], v141 offset:3072
	v_lshl_add_u64 v[154:155], s[42:43], 0, v[136:137]
	s_add_i32 m0, s49, 0xc000
	ds_read_b128 v[198:201], v149
	ds_read_b128 v[202:205], v149 offset:1024
	ds_read_b128 v[206:209], v149 offset:2048
	ds_read_b128 v[210:213], v149 offset:3072
	ds_read_b128 v[214:217], v149 offset:4096
	ds_read_b128 v[218:221], v149 offset:5120
	ds_read_b128 v[222:225], v149 offset:6144
	ds_read_b128 v[226:229], v149 offset:7168
	global_load_lds_dwordx4 v[154:155], off
	v_lshl_add_u64 v[154:155], s[42:43], 0, v[138:139]
	s_add_i32 m0, s49, 0xe000
	s_nop 0
	global_load_lds_dwordx4 v[154:155], off
	s_waitcnt vmcnt(8)
	s_waitcnt lgkmcnt(0)
	s_barrier
	s_setprio 0
	s_waitcnt lgkmcnt(0)
	v_mfma_f32_16x16x32_bf16 v[124:127], v[150:153], v[198:201], v[124:127]
	v_mfma_f32_16x16x32_bf16 v[120:123], v[174:177], v[198:201], v[120:123]
	v_mfma_f32_16x16x32_bf16 v[108:111], v[150:153], v[206:209], v[108:111]
	v_mfma_f32_16x16x32_bf16 v[104:107], v[174:177], v[206:209], v[104:107]
	v_mfma_f32_16x16x32_bf16 v[96:99], v[150:153], v[214:217], v[96:99]
	v_mfma_f32_16x16x32_bf16 v[88:91], v[174:177], v[214:217], v[88:91]
	v_mfma_f32_16x16x32_bf16 v[80:83], v[150:153], v[222:225], v[80:83]
	v_mfma_f32_16x16x32_bf16 v[72:75], v[174:177], v[222:225], v[72:75]
	v_mfma_f32_16x16x32_bf16 v[124:127], v[170:173], v[202:205], v[124:127]
	v_mfma_f32_16x16x32_bf16 v[120:123], v[178:181], v[202:205], v[120:123]
	v_mfma_f32_16x16x32_bf16 v[108:111], v[170:173], v[210:213], v[108:111]
	v_mfma_f32_16x16x32_bf16 v[104:107], v[178:181], v[210:213], v[104:107]
	v_mfma_f32_16x16x32_bf16 v[96:99], v[170:173], v[218:221], v[96:99]
	v_mfma_f32_16x16x32_bf16 v[88:91], v[178:181], v[218:221], v[88:91]
	v_mfma_f32_16x16x32_bf16 v[80:83], v[170:173], v[226:229], v[80:83]
	v_mfma_f32_16x16x32_bf16 v[72:75], v[178:181], v[226:229], v[72:75]
	s_setprio 1
	s_setprio 0
	v_mfma_f32_16x16x32_bf16 v[116:119], v[182:185], v[198:201], v[116:119]
	v_mfma_f32_16x16x32_bf16 v[112:115], v[190:193], v[198:201], v[112:115]
	v_mfma_f32_16x16x32_bf16 v[100:103], v[182:185], v[206:209], v[100:103]
	v_mfma_f32_16x16x32_bf16 v[92:95], v[190:193], v[206:209], v[92:95]
	v_mfma_f32_16x16x32_bf16 v[84:87], v[182:185], v[214:217], v[84:87]
	v_mfma_f32_16x16x32_bf16 v[76:79], v[190:193], v[214:217], v[76:79]
	v_mfma_f32_16x16x32_bf16 v[68:71], v[182:185], v[222:225], v[68:71]
	v_mfma_f32_16x16x32_bf16 v[64:67], v[190:193], v[222:225], v[64:67]
	v_mfma_f32_16x16x32_bf16 v[116:119], v[186:189], v[202:205], v[116:119]
	v_mfma_f32_16x16x32_bf16 v[112:115], v[194:197], v[202:205], v[112:115]
	v_mfma_f32_16x16x32_bf16 v[100:103], v[186:189], v[210:213], v[100:103]
	v_mfma_f32_16x16x32_bf16 v[92:95], v[194:197], v[210:213], v[92:95]
	v_mfma_f32_16x16x32_bf16 v[84:87], v[186:189], v[218:221], v[84:87]
	v_mfma_f32_16x16x32_bf16 v[76:79], v[194:197], v[218:221], v[76:79]
	v_mfma_f32_16x16x32_bf16 v[68:71], v[186:189], v[226:229], v[68:71]
	v_mfma_f32_16x16x32_bf16 v[64:67], v[194:197], v[226:229], v[64:67]
	s_setprio 1
	s_barrier
	s_add_i32 s63, s63, s34
	v_lshl_add_u64 v[154:155], s[44:45], 0, v[132:133]
	s_mov_b32 m0, s63
	ds_read_b128 v[198:201], v149 offset:16384
	ds_read_b128 v[202:205], v149 offset:17408
	ds_read_b128 v[206:209], v149 offset:18432
	ds_read_b128 v[210:213], v149 offset:19456
	ds_read_b128 v[214:217], v149 offset:20480
	ds_read_b128 v[218:221], v149 offset:21504
	ds_read_b128 v[222:225], v149 offset:22528
	ds_read_b128 v[226:229], v149 offset:23552
	global_load_lds_dwordx4 v[154:155], off
	s_add_i32 m0, s63, 0x2000
	s_add_u32 s64, s44, 0x40000
	v_lshl_add_u64 v[236:237], s[44:45], 0, v[128:129]
	s_addc_u32 s65, s45, 0
	s_add_i32 s63, s66, s34
	global_load_lds_dwordx4 v[236:237], off
	v_lshl_add_u64 v[238:239], s[64:65], 0, v[132:133]
	s_mov_b32 m0, s63
	v_lshl_add_u64 v[240:241], s[46:47], 0, v[130:131]
	global_load_lds_dwordx4 v[238:239], off
	v_lshl_add_u64 v[238:239], s[64:65], 0, v[128:129]
	s_add_i32 m0, s63, 0x2000
	s_nop 0
	global_load_lds_dwordx4 v[238:239], off
	v_lshl_add_u64 v[238:239], s[46:47], 0, v[134:135]
	s_mov_b32 m0, s49
	s_nop 0
	global_load_lds_dwordx4 v[238:239], off
	s_mov_b32 m0, s50
	s_nop 0
	global_load_lds_dwordx4 v[240:241], off
	s_waitcnt vmcnt(8)
	s_waitcnt lgkmcnt(0)
	s_barrier
; #define PG8_STAGE(bufoff, gbase, voff) do { _Pragma("unroll") for (int _i = 0; _i < 2; ++_i) \
;         __builtin_amdgcn_global_load_lds((const unsigned*)((const char*)(gbase) + (voff)[_i]), (PG8_LAS unsigned*)(lds + (bufoff) + ldsw + _i * 8192), 16, 0, 0); } while (0)
; #define PG8_LDA(dst, b, h) do { _Pragma("unroll") for (int m = 0; m < 4; ++m) _Pragma("unroll") for (int k = 0; k < 2; ++k) dst[m][k] = *(const PG8_LAS bf16x8*)(lds + PG8_SA(b, h) + aoff + m * 2048 + k * 1024); } while (0)
; #define PG8_LDB(dst, b, h) do { _Pragma("unroll") for (int n = 0; n < 2; ++n) _Pragma("unroll") for (int k = 0; k < 2; ++k) dst[n][k] = *(const PG8_LAS bf16x8*)(lds + PG8_SB(b, h) + boff + n * 2048 + k * 1024); } while (0)
; #define PG8_MMA(ai, bj, At, Bt) do { __builtin_amdgcn_s_setprio(1); _Pragma("unroll") for (int m = 0; m < 4; ++m) _Pragma("unroll") for (int n = 0; n < 2; ++n) _Pragma("unroll") for (int k = 0; k < 2; ++k) \
;         acc[ai][bj][m][n] = __builtin_amdgcn_mfma_f32_16x16x32_bf16(Bt[n][k], At[m][k], acc[ai][bj][m][n], 0, 0, 0); __builtin_amdgcn_s_setprio(0); } while (0)
; #define PG8_WAIT_V(n) asm volatile("s_waitcnt vmcnt(" #n ")" ::: "memory")
; #define PG8_WAIT_L(n) asm volatile("s_waitcnt lgkmcnt(" #n ")" ::: "memory")
; #define PG8_BAR __builtin_amdgcn_s_barrier()
; #define PG8_SCHED __builtin_amdgcn_sched_barrier(0)
; template <class Epi, class Sched, bool ALIGN_EPI = false, bool SP2 = false>
; __device__ __forceinline__ void gemm_phase(PG8_LAS unsigned char* lds, const Gemm g, const Sched& S, const Epi& E) {
;     ...
;             PG8_WAIT_V(8); PG8_WAIT_L(0); PG8_BAR; PG8_MMA(1, 0, At, B0); PG8_MMA(1, 1, At, B1); PG8_BAR; PG8_SCHED;
;             PG8_LDB(B0, 1, 0); PG8_LDB(B1, 1, 1); PG8_SCHED; PG8_LDA(At, 1, 0); PG8_STAGE(PG8_SA(0, 1), a2 + hstep, voffA);
;             PG8_WAIT_V(8); PG8_WAIT_L(0); PG8_BAR; PG8_MMA(0, 0, At, B0); PG8_MMA(0, 1, At, B1); PG8_BAR; PG8_SCHED;
	s_setprio 0
	s_waitcnt lgkmcnt(0)
	v_mfma_f32_16x16x32_bf16 v[60:63], v[150:153], v[198:201], v[60:63]
	v_mfma_f32_16x16x32_bf16 v[56:59], v[174:177], v[198:201], v[56:59]
	v_mfma_f32_16x16x32_bf16 v[44:47], v[150:153], v[206:209], v[44:47]
	v_mfma_f32_16x16x32_bf16 v[40:43], v[174:177], v[206:209], v[40:43]
	v_mfma_f32_16x16x32_bf16 v[32:35], v[150:153], v[214:217], v[32:35]
	v_mfma_f32_16x16x32_bf16 v[24:27], v[174:177], v[214:217], v[24:27]
	v_mfma_f32_16x16x32_bf16 v[16:19], v[150:153], v[222:225], v[16:19]
	v_mfma_f32_16x16x32_bf16 v[8:11], v[174:177], v[222:225], v[8:11]
	v_mfma_f32_16x16x32_bf16 v[60:63], v[170:173], v[202:205], v[60:63]
	v_mfma_f32_16x16x32_bf16 v[56:59], v[178:181], v[202:205], v[56:59]
	v_mfma_f32_16x16x32_bf16 v[44:47], v[170:173], v[210:213], v[44:47]
	v_mfma_f32_16x16x32_bf16 v[40:43], v[178:181], v[210:213], v[40:43]
	v_mfma_f32_16x16x32_bf16 v[32:35], v[170:173], v[218:221], v[32:35]
	v_mfma_f32_16x16x32_bf16 v[24:27], v[178:181], v[218:221], v[24:27]
	v_mfma_f32_16x16x32_bf16 v[16:19], v[170:173], v[226:229], v[16:19]
	v_mfma_f32_16x16x32_bf16 v[8:11], v[178:181], v[226:229], v[8:11]
	s_setprio 1
	s_setprio 0
	v_mfma_f32_16x16x32_bf16 v[52:55], v[182:185], v[198:201], v[52:55]
	v_mfma_f32_16x16x32_bf16 v[48:51], v[190:193], v[198:201], v[48:51]
	v_mfma_f32_16x16x32_bf16 v[36:39], v[182:185], v[206:209], v[36:39]
	v_mfma_f32_16x16x32_bf16 v[28:31], v[190:193], v[206:209], v[28:31]
	v_mfma_f32_16x16x32_bf16 v[20:23], v[182:185], v[214:217], v[20:23]
	v_mfma_f32_16x16x32_bf16 v[12:15], v[190:193], v[214:217], v[12:15]
	v_mfma_f32_16x16x32_bf16 v[4:7], v[182:185], v[222:225], v[4:7]
	v_mfma_f32_16x16x32_bf16 v[0:3], v[190:193], v[222:225], v[0:3]
	v_mfma_f32_16x16x32_bf16 v[52:55], v[186:189], v[202:205], v[52:55]
	v_mfma_f32_16x16x32_bf16 v[48:51], v[194:197], v[202:205], v[48:51]
	v_mfma_f32_16x16x32_bf16 v[36:39], v[186:189], v[210:213], v[36:39]
	v_mfma_f32_16x16x32_bf16 v[28:31], v[194:197], v[210:213], v[28:31]
	v_mfma_f32_16x16x32_bf16 v[20:23], v[186:189], v[218:221], v[20:23]
	v_mfma_f32_16x16x32_bf16 v[12:15], v[194:197], v[218:221], v[12:15]
	v_mfma_f32_16x16x32_bf16 v[4:7], v[186:189], v[226:229], v[4:7]
	v_mfma_f32_16x16x32_bf16 v[0:3], v[194:197], v[226:229], v[0:3]
	s_setprio 1
	s_barrier
	s_add_i32 s63, 0, 0x18000
	v_add_u32_e32 v141, s63, v145
	s_add_i32 s64, 0, 0x1c000
	ds_read_b128 v[150:153], v141
	ds_read_b128 v[170:173], v141 offset:1024
	ds_read_b128 v[174:177], v141 offset:2048
	ds_read_b128 v[178:181], v141 offset:3072
	v_add_u32_e32 v141, s64, v145
	ds_read_b128 v[182:185], v141
	ds_read_b128 v[186:189], v141 offset:1024
	ds_read_b128 v[190:193], v141 offset:2048
	ds_read_b128 v[194:197], v141 offset:3072
	s_add_u32 s46, s46, 0x40000
	s_addc_u32 s47, s47, 0
	s_mov_b32 m0, s51
	v_lshl_add_u64 v[242:243], s[46:47], 0, v[134:135]
	ds_read_b128 v[198:201], v149 offset:32768
	ds_read_b128 v[202:205], v149 offset:33792
	ds_read_b128 v[206:209], v149 offset:34816
	ds_read_b128 v[210:213], v149 offset:35840
	ds_read_b128 v[214:217], v149 offset:36864
	ds_read_b128 v[218:221], v149 offset:37888
	ds_read_b128 v[222:225], v149 offset:38912
	ds_read_b128 v[226:229], v149 offset:39936
	global_load_lds_dwordx4 v[242:243], off
	v_lshl_add_u64 v[242:243], s[46:47], 0, v[130:131]
	s_mov_b32 m0, s52
	s_nop 0
	global_load_lds_dwordx4 v[242:243], off
	s_waitcnt vmcnt(8)
	s_waitcnt lgkmcnt(0)
	s_barrier
	s_setprio 0
	s_waitcnt lgkmcnt(0)
	v_mfma_f32_16x16x32_bf16 v[124:127], v[150:153], v[198:201], v[124:127]
	v_mfma_f32_16x16x32_bf16 v[120:123], v[174:177], v[198:201], v[120:123]
	v_mfma_f32_16x16x32_bf16 v[108:111], v[150:153], v[206:209], v[108:111]
	v_mfma_f32_16x16x32_bf16 v[104:107], v[174:177], v[206:209], v[104:107]
	v_mfma_f32_16x16x32_bf16 v[96:99], v[150:153], v[214:217], v[96:99]
	v_mfma_f32_16x16x32_bf16 v[88:91], v[174:177], v[214:217], v[88:91]
	v_mfma_f32_16x16x32_bf16 v[80:83], v[150:153], v[222:225], v[80:83]
	v_mfma_f32_16x16x32_bf16 v[72:75], v[174:177], v[222:225], v[72:75]
	v_mfma_f32_16x16x32_bf16 v[124:127], v[170:173], v[202:205], v[124:127]
	v_mfma_f32_16x16x32_bf16 v[120:123], v[178:181], v[202:205], v[120:123]
	v_mfma_f32_16x16x32_bf16 v[108:111], v[170:173], v[210:213], v[108:111]
	v_mfma_f32_16x16x32_bf16 v[104:107], v[178:181], v[210:213], v[104:107]
	v_mfma_f32_16x16x32_bf16 v[96:99], v[170:173], v[218:221], v[96:99]
	v_mfma_f32_16x16x32_bf16 v[88:91], v[178:181], v[218:221], v[88:91]
	v_mfma_f32_16x16x32_bf16 v[80:83], v[170:173], v[226:229], v[80:83]
	v_mfma_f32_16x16x32_bf16 v[72:75], v[178:181], v[226:229], v[72:75]
	s_setprio 1
	s_setprio 0
	v_mfma_f32_16x16x32_bf16 v[116:119], v[182:185], v[198:201], v[116:119]
	v_mfma_f32_16x16x32_bf16 v[112:115], v[190:193], v[198:201], v[112:115]
	v_mfma_f32_16x16x32_bf16 v[100:103], v[182:185], v[206:209], v[100:103]
	v_mfma_f32_16x16x32_bf16 v[92:95], v[190:193], v[206:209], v[92:95]
	v_mfma_f32_16x16x32_bf16 v[84:87], v[182:185], v[214:217], v[84:87]
	v_mfma_f32_16x16x32_bf16 v[76:79], v[190:193], v[214:217], v[76:79]
	v_mfma_f32_16x16x32_bf16 v[68:71], v[182:185], v[222:225], v[68:71]
	v_mfma_f32_16x16x32_bf16 v[64:67], v[190:193], v[222:225], v[64:67]
	v_mfma_f32_16x16x32_bf16 v[116:119], v[186:189], v[202:205], v[116:119]
	v_mfma_f32_16x16x32_bf16 v[112:115], v[194:197], v[202:205], v[112:115]
	v_mfma_f32_16x16x32_bf16 v[100:103], v[186:189], v[210:213], v[100:103]
	v_mfma_f32_16x16x32_bf16 v[92:95], v[194:197], v[210:213], v[92:95]
	v_mfma_f32_16x16x32_bf16 v[84:87], v[186:189], v[218:221], v[84:87]
	v_mfma_f32_16x16x32_bf16 v[76:79], v[194:197], v[218:221], v[76:79]
	v_mfma_f32_16x16x32_bf16 v[68:71], v[186:189], v[226:229], v[68:71]
	v_mfma_f32_16x16x32_bf16 v[64:67], v[194:197], v[226:229], v[64:67]
	s_setprio 1
	s_barrier
; #define PG8_STAGE(bufoff, gbase, voff) do { _Pragma("unroll") for (int _i = 0; _i < 2; ++_i) \
;         __builtin_amdgcn_global_load_lds((const unsigned*)((const char*)(gbase) + (voff)[_i]), (PG8_LAS unsigned*)(lds + (bufoff) + ldsw + _i * 8192), 16, 0, 0); } while (0)
; #define PG8_LDA(dst, b, h) do { _Pragma("unroll") for (int m = 0; m < 4; ++m) _Pragma("unroll") for (int k = 0; k < 2; ++k) dst[m][k] = *(const PG8_LAS bf16x8*)(lds + PG8_SA(b, h) + aoff + m * 2048 + k * 1024); } while (0)
; #define PG8_MMA(ai, bj, At, Bt) do { __builtin_amdgcn_s_setprio(1); _Pragma("unroll") for (int m = 0; m < 4; ++m) _Pragma("unroll") for (int n = 0; n < 2; ++n) _Pragma("unroll") for (int k = 0; k < 2; ++k) \
;         acc[ai][bj][m][n] = __builtin_amdgcn_mfma_f32_16x16x32_bf16(Bt[n][k], At[m][k], acc[ai][bj][m][n], 0, 0, 0); __builtin_amdgcn_s_setprio(0); } while (0)
; #define PG8_WAIT_V(n) asm volatile("s_waitcnt vmcnt(" #n ")" ::: "memory")
; #define PG8_WAIT_L(n) asm volatile("s_waitcnt lgkmcnt(" #n ")" ::: "memory")
; #define PG8_BAR __builtin_amdgcn_s_barrier()
; #define PG8_SCHED __builtin_amdgcn_sched_barrier(0)
; template <class Epi, class Sched, bool ALIGN_EPI = false, bool SP2 = false>
; __device__ __forceinline__ void gemm_phase(PG8_LAS unsigned char* lds, const Gemm g, const Sched& S, const Epi& E) {
;     ...
;             PG8_LDA(At, 1, 1); PG8_STAGE(PG8_SB(1, 0), b3, voffB); PG8_STAGE(PG8_SB(1, 1), b3 + hstep, voffB); PG8_STAGE(PG8_SA(1, 0), a3, voffA);
;             PG8_WAIT_V(8); PG8_WAIT_L(0); PG8_BAR; PG8_MMA(1, 0, At, B0); PG8_MMA(1, 1, At, B1); PG8_BAR; PG8_SCHED;
	s_add_i32 s46, s63, s34
	v_lshl_add_u64 v[154:155], v[154:155], 0, s[96:97]
	s_mov_b32 m0, s46
	ds_read_b128 v[198:201], v149 offset:49152
	ds_read_b128 v[202:205], v149 offset:50176
	ds_read_b128 v[206:209], v149 offset:51200
	ds_read_b128 v[210:213], v149 offset:52224
	ds_read_b128 v[214:217], v149 offset:53248
	ds_read_b128 v[218:221], v149 offset:54272
	ds_read_b128 v[222:225], v149 offset:55296
	ds_read_b128 v[226:229], v149 offset:56320
	global_load_lds_dwordx4 v[154:155], off
	s_add_i32 m0, s46, 0x2000
	s_add_u32 s44, s44, 0x40080
	v_lshl_add_u64 v[154:155], v[236:237], 0, s[96:97]
	s_addc_u32 s45, s45, 0
	s_add_i32 s46, s64, s34
	global_load_lds_dwordx4 v[154:155], off
	v_lshl_add_u64 v[154:155], s[44:45], 0, v[132:133]
	s_mov_b32 m0, s46
	s_nop 0
	global_load_lds_dwordx4 v[154:155], off
	v_lshl_add_u64 v[154:155], s[44:45], 0, v[128:129]
	s_add_i32 m0, s46, 0x2000
	s_nop 0
	global_load_lds_dwordx4 v[154:155], off
	v_lshl_add_u64 v[154:155], v[238:239], 0, s[96:97]
	s_mov_b32 m0, s58
	s_nop 0
	global_load_lds_dwordx4 v[154:155], off
	v_lshl_add_u64 v[154:155], v[240:241], 0, s[96:97]
	s_mov_b32 m0, s59
	s_nop 0
	global_load_lds_dwordx4 v[154:155], off
	s_waitcnt vmcnt(8)
	s_waitcnt lgkmcnt(0)
	s_barrier
	s_setprio 0
	s_waitcnt lgkmcnt(0)
	v_mfma_f32_16x16x32_bf16 v[60:63], v[150:153], v[198:201], v[60:63]
	v_mfma_f32_16x16x32_bf16 v[56:59], v[174:177], v[198:201], v[56:59]
	v_mfma_f32_16x16x32_bf16 v[44:47], v[150:153], v[206:209], v[44:47]
	v_mfma_f32_16x16x32_bf16 v[40:43], v[174:177], v[206:209], v[40:43]
	v_mfma_f32_16x16x32_bf16 v[32:35], v[150:153], v[214:217], v[32:35]
	v_mfma_f32_16x16x32_bf16 v[24:27], v[174:177], v[214:217], v[24:27]
	v_mfma_f32_16x16x32_bf16 v[16:19], v[150:153], v[222:225], v[16:19]
	v_mfma_f32_16x16x32_bf16 v[8:11], v[174:177], v[222:225], v[8:11]
	v_mfma_f32_16x16x32_bf16 v[60:63], v[170:173], v[202:205], v[60:63]
	v_mfma_f32_16x16x32_bf16 v[56:59], v[178:181], v[202:205], v[56:59]
	v_mfma_f32_16x16x32_bf16 v[44:47], v[170:173], v[210:213], v[44:47]
	v_mfma_f32_16x16x32_bf16 v[40:43], v[178:181], v[210:213], v[40:43]
	v_mfma_f32_16x16x32_bf16 v[32:35], v[170:173], v[218:221], v[32:35]
	v_mfma_f32_16x16x32_bf16 v[24:27], v[178:181], v[218:221], v[24:27]
	v_mfma_f32_16x16x32_bf16 v[16:19], v[170:173], v[226:229], v[16:19]
	v_mfma_f32_16x16x32_bf16 v[8:11], v[178:181], v[226:229], v[8:11]
	s_setprio 1
	s_setprio 0
	v_mfma_f32_16x16x32_bf16 v[52:55], v[182:185], v[198:201], v[52:55]
	v_mfma_f32_16x16x32_bf16 v[48:51], v[190:193], v[198:201], v[48:51]
	v_mfma_f32_16x16x32_bf16 v[36:39], v[182:185], v[206:209], v[36:39]
	v_mfma_f32_16x16x32_bf16 v[28:31], v[190:193], v[206:209], v[28:31]
	v_mfma_f32_16x16x32_bf16 v[20:23], v[182:185], v[214:217], v[20:23]
	v_mfma_f32_16x16x32_bf16 v[12:15], v[190:193], v[214:217], v[12:15]
	v_mfma_f32_16x16x32_bf16 v[4:7], v[182:185], v[222:225], v[4:7]
	v_mfma_f32_16x16x32_bf16 v[0:3], v[190:193], v[222:225], v[0:3]
	v_mfma_f32_16x16x32_bf16 v[52:55], v[186:189], v[202:205], v[52:55]
	v_mfma_f32_16x16x32_bf16 v[48:51], v[194:197], v[202:205], v[48:51]
	v_mfma_f32_16x16x32_bf16 v[36:39], v[186:189], v[210:213], v[36:39]
	v_mfma_f32_16x16x32_bf16 v[28:31], v[194:197], v[210:213], v[28:31]
	v_mfma_f32_16x16x32_bf16 v[20:23], v[186:189], v[218:221], v[20:23]
	v_mfma_f32_16x16x32_bf16 v[12:15], v[194:197], v[218:221], v[12:15]
	v_mfma_f32_16x16x32_bf16 v[4:7], v[186:189], v[226:229], v[4:7]
	v_mfma_f32_16x16x32_bf16 v[0:3], v[194:197], v[226:229], v[0:3]
	s_setprio 1
	s_barrier
	s_add_i32 s62, s62, 2
	s_add_u32 s42, s42, 0x100
	s_addc_u32 s43, s43, 0
	s_add_u32 s60, s60, 0x100
	s_addc_u32 s61, s61, 0
	s_cmp_gt_u32 s62, 13
	s_cbranch_scc0 .LBB0_237
	s_and_b64 vcc, exec, s[8:9]
	s_cbranch_vccz .LBB0_240
	s_barrier

; #define PG8_STAGE(bufoff, gbase, voff) do { _Pragma("unroll") for (int _i = 0; _i < 2; ++_i) \
;         __builtin_amdgcn_global_load_lds((const unsigned*)((const char*)(gbase) + (voff)[_i]), (PG8_LAS unsigned*)(lds + (bufoff) + ldsw + _i * 8192), 16, 0, 0); } while (0)
; #define PG8_LDA(dst, b, h) do { _Pragma("unroll") for (int m = 0; m < 4; ++m) _Pragma("unroll") for (int k = 0; k < 2; ++k) dst[m][k] = *(const PG8_LAS bf16x8*)(lds + PG8_SA(b, h) + aoff + m * 2048 + k * 1024); } while (0)
; #define PG8_LDB(dst, b, h) do { _Pragma("unroll") for (int n = 0; n < 2; ++n) _Pragma("unroll") for (int k = 0; k < 2; ++k) dst[n][k] = *(const PG8_LAS bf16x8*)(lds + PG8_SB(b, h) + boff + n * 2048 + k * 1024); } while (0)
; #define PG8_MMA(ai, bj, At, Bt) do { __builtin_amdgcn_s_setprio(1); _Pragma("unroll") for (int m = 0; m < 4; ++m) _Pragma("unroll") for (int n = 0; n < 2; ++n) _Pragma("unroll") for (int k = 0; k < 2; ++k) \
;         acc[ai][bj][m][n] = __builtin_amdgcn_mfma_f32_16x16x32_bf16(Bt[n][k], At[m][k], acc[ai][bj][m][n], 0, 0, 0); __builtin_amdgcn_s_setprio(0); } while (0)
; #define PG8_WAIT_V(n) asm volatile("s_waitcnt vmcnt(" #n ")" ::: "memory")
; #define PG8_WAIT_L(n) asm volatile("s_waitcnt lgkmcnt(" #n ")" ::: "memory")
; #define PG8_BAR __builtin_amdgcn_s_barrier()
; #define PG8_SCHED __builtin_amdgcn_sched_barrier(0)
; template <class Epi, class Sched, bool ALIGN_EPI = false, bool SP2 = false>
; __device__ __forceinline__ void gemm_phase(PG8_LAS unsigned char* lds, const Gemm g, const Sched& S, const Epi& E) {
;     ...
;             const bool last = (t == nt - 2);
;             const char* a1 = cA + (size_t)(t + 1) * kstep;
;             const char* a2 = last ? nA : cA + (size_t)(t + 2) * kstep; const char* b2 = last ? nB : cB + (size_t)(t + 2) * kstep;
;             const char* a3 = a2 + kstep; const char* b3 = b2 + kstep;
;             if (last && has_next) S.a_ready(nxt);
;             if constexpr (SP2) {
;             PG8_LDB(B0, 0, 0); PG8_LDB(B1, 0, 1); PG8_SCHED; PG8_LDA(At, 0, 0); PG8_STAGE(PG8_SA(1, 1), a1 + hstep, voffA);
;             PG8_WAIT_V(8); PG8_WAIT_L(0); PG8_BAR; PG8_MMA(0, 0, At, B0); PG8_MMA(0, 1, At, B1); PG8_BAR; PG8_SCHED;
;             PG8_LDA(At, 0, 1); PG8_STAGE(PG8_SB(0, 0), b2, voffB); PG8_STAGE(PG8_SB(0, 1), b2 + hstep, voffB); PG8_STAGE(PG8_SA(0, 0), a2, voffA);
.LBB0_264:
	s_add_u32 s12, s10, 0x100
	s_addc_u32 s13, s11, 0
	s_add_i32 s34, 0, 0x10000
	s_cmp_eq_u32 s31, 40
	s_cselect_b32 s17, s7, s13
	s_cselect_b32 s16, s6, s12
	s_cselect_b32 s15, s9, s30
	s_cselect_b32 s14, s8, s29
	s_add_i32 s35, 0, 0x14000
	v_add_u32_e32 v132, s34, v169
	v_add_u32_e32 v180, s35, v169
	ds_read_b128 v[104:107], v132
	ds_read_b128 v[120:123], v132 offset:1024
	ds_read_b128 v[128:131], v132 offset:2048
	ds_read_b128 v[132:135], v132 offset:3072
	ds_read_b128 v[136:139], v180
	ds_read_b128 v[148:151], v180 offset:1024
	ds_read_b128 v[152:155], v180 offset:2048
	ds_read_b128 v[180:183], v180 offset:3072
	v_lshl_add_u64 v[216:217], s[10:11], 0, v[176:177]
	s_add_i32 m0, s21, 0xc000
	ds_read_b128 v[184:187], v239
	ds_read_b128 v[188:191], v239 offset:1024
	ds_read_b128 v[192:195], v239 offset:2048
	ds_read_b128 v[196:199], v239 offset:3072
	ds_read_b128 v[200:203], v239 offset:4096
	ds_read_b128 v[204:207], v239 offset:5120
	ds_read_b128 v[208:211], v239 offset:6144
	ds_read_b128 v[212:215], v239 offset:7168
	global_load_lds_dwordx4 v[216:217], off
	v_lshl_add_u64 v[216:217], s[10:11], 0, v[178:179]
	s_add_i32 m0, s21, 0xe000
	s_nop 0
	global_load_lds_dwordx4 v[216:217], off
	s_waitcnt vmcnt(8)
	s_waitcnt lgkmcnt(0)
	s_barrier
	s_setprio 0
	s_waitcnt lgkmcnt(0)
	v_mfma_f32_16x16x32_bf16 v[144:147], v[104:107], v[184:187], v[144:147]
	v_mfma_f32_16x16x32_bf16 v[140:143], v[128:131], v[184:187], v[140:143]
	v_mfma_f32_16x16x32_bf16 v[112:115], v[104:107], v[192:195], v[112:115]
	v_mfma_f32_16x16x32_bf16 v[108:111], v[128:131], v[192:195], v[108:111]
	v_mfma_f32_16x16x32_bf16 v[92:95], v[104:107], v[200:203], v[92:95]
	v_mfma_f32_16x16x32_bf16 v[88:91], v[128:131], v[200:203], v[88:91]
	v_mfma_f32_16x16x32_bf16 v[76:79], v[104:107], v[208:211], v[76:79]
	v_mfma_f32_16x16x32_bf16 v[72:75], v[128:131], v[208:211], v[72:75]
	v_mfma_f32_16x16x32_bf16 v[144:147], v[120:123], v[188:191], v[144:147]
	v_mfma_f32_16x16x32_bf16 v[140:143], v[132:135], v[188:191], v[140:143]
	v_mfma_f32_16x16x32_bf16 v[112:115], v[120:123], v[196:199], v[112:115]
	v_mfma_f32_16x16x32_bf16 v[108:111], v[132:135], v[196:199], v[108:111]
	v_mfma_f32_16x16x32_bf16 v[92:95], v[120:123], v[204:207], v[92:95]
	v_mfma_f32_16x16x32_bf16 v[88:91], v[132:135], v[204:207], v[88:91]
	v_mfma_f32_16x16x32_bf16 v[76:79], v[120:123], v[212:215], v[76:79]
	v_mfma_f32_16x16x32_bf16 v[72:75], v[132:135], v[212:215], v[72:75]
	s_setprio 1
	s_setprio 0
	v_mfma_f32_16x16x32_bf16 v[124:127], v[136:139], v[184:187], v[124:127]
	v_mfma_f32_16x16x32_bf16 v[116:119], v[152:155], v[184:187], v[116:119]
	v_mfma_f32_16x16x32_bf16 v[100:103], v[136:139], v[192:195], v[100:103]
	v_mfma_f32_16x16x32_bf16 v[96:99], v[152:155], v[192:195], v[96:99]
	v_mfma_f32_16x16x32_bf16 v[84:87], v[136:139], v[200:203], v[84:87]
	v_mfma_f32_16x16x32_bf16 v[80:83], v[152:155], v[200:203], v[80:83]
	v_mfma_f32_16x16x32_bf16 v[68:71], v[136:139], v[208:211], v[68:71]
	v_mfma_f32_16x16x32_bf16 v[64:67], v[152:155], v[208:211], v[64:67]
	v_mfma_f32_16x16x32_bf16 v[124:127], v[148:151], v[188:191], v[124:127]
	v_mfma_f32_16x16x32_bf16 v[116:119], v[180:183], v[188:191], v[116:119]
	v_mfma_f32_16x16x32_bf16 v[100:103], v[148:151], v[196:199], v[100:103]
	v_mfma_f32_16x16x32_bf16 v[96:99], v[180:183], v[196:199], v[96:99]
	v_mfma_f32_16x16x32_bf16 v[84:87], v[148:151], v[204:207], v[84:87]
	v_mfma_f32_16x16x32_bf16 v[80:83], v[180:183], v[204:207], v[80:83]
	v_mfma_f32_16x16x32_bf16 v[68:71], v[148:151], v[212:215], v[68:71]
	v_mfma_f32_16x16x32_bf16 v[64:67], v[180:183], v[212:215], v[64:67]
	s_setprio 1
	s_barrier
	s_add_i32 s10, s34, s20
	v_lshl_add_u64 v[216:217], s[14:15], 0, v[156:157]
	s_mov_b32 m0, s10
	ds_read_b128 v[184:187], v239 offset:16384
	ds_read_b128 v[188:191], v239 offset:17408
	ds_read_b128 v[192:195], v239 offset:18432
	ds_read_b128 v[196:199], v239 offset:19456
	ds_read_b128 v[200:203], v239 offset:20480
	ds_read_b128 v[204:207], v239 offset:21504
	ds_read_b128 v[208:211], v239 offset:22528
	ds_read_b128 v[212:215], v239 offset:23552
	global_load_lds_dwordx4 v[216:217], off
	s_add_i32 m0, s10, 0x2000
	s_add_u32 s10, s14, 0xb0000
	v_lshl_add_u64 v[218:219], s[14:15], 0, v[170:171]
	s_addc_u32 s11, s15, 0
	s_add_i32 s34, s35, s20
	global_load_lds_dwordx4 v[218:219], off
	v_lshl_add_u64 v[220:221], s[10:11], 0, v[156:157]
	s_mov_b32 m0, s34
	v_lshl_add_u64 v[222:223], s[16:17], 0, v[172:173]
	global_load_lds_dwordx4 v[220:221], off
	v_lshl_add_u64 v[220:221], s[10:11], 0, v[170:171]
	s_add_i32 m0, s34, 0x2000
	s_nop 0
	global_load_lds_dwordx4 v[220:221], off
	v_lshl_add_u64 v[220:221], s[16:17], 0, v[174:175]
	s_mov_b32 m0, s21
	s_nop 0
	global_load_lds_dwordx4 v[220:221], off
	s_mov_b32 m0, s27
	s_nop 0
	global_load_lds_dwordx4 v[222:223], off
	s_waitcnt vmcnt(8)
	s_waitcnt lgkmcnt(0)
	s_barrier
; #define PG8_STAGE(bufoff, gbase, voff) do { _Pragma("unroll") for (int _i = 0; _i < 2; ++_i) \
;         __builtin_amdgcn_global_load_lds((const unsigned*)((const char*)(gbase) + (voff)[_i]), (PG8_LAS unsigned*)(lds + (bufoff) + ldsw + _i * 8192), 16, 0, 0); } while (0)
; #define PG8_LDA(dst, b, h) do { _Pragma("unroll") for (int m = 0; m < 4; ++m) _Pragma("unroll") for (int k = 0; k < 2; ++k) dst[m][k] = *(const PG8_LAS bf16x8*)(lds + PG8_SA(b, h) + aoff + m * 2048 + k * 1024); } while (0)
; #define PG8_LDB(dst, b, h) do { _Pragma("unroll") for (int n = 0; n < 2; ++n) _Pragma("unroll") for (int k = 0; k < 2; ++k) dst[n][k] = *(const PG8_LAS bf16x8*)(lds + PG8_SB(b, h) + boff + n * 2048 + k * 1024); } while (0)
; #define PG8_MMA(ai, bj, At, Bt) do { __builtin_amdgcn_s_setprio(1); _Pragma("unroll") for (int m = 0; m < 4; ++m) _Pragma("unroll") for (int n = 0; n < 2; ++n) _Pragma("unroll") for (int k = 0; k < 2; ++k) \
;         acc[ai][bj][m][n] = __builtin_amdgcn_mfma_f32_16x16x32_bf16(Bt[n][k], At[m][k], acc[ai][bj][m][n], 0, 0, 0); __builtin_amdgcn_s_setprio(0); } while (0)
; #define PG8_WAIT_V(n) asm volatile("s_waitcnt vmcnt(" #n ")" ::: "memory")
; #define PG8_WAIT_L(n) asm volatile("s_waitcnt lgkmcnt(" #n ")" ::: "memory")
; #define PG8_BAR __builtin_amdgcn_s_barrier()
; #define PG8_SCHED __builtin_amdgcn_sched_barrier(0)
; template <class Epi, class Sched, bool ALIGN_EPI = false, bool SP2 = false>
; __device__ __forceinline__ void gemm_phase(PG8_LAS unsigned char* lds, const Gemm g, const Sched& S, const Epi& E) {
;     ...
;             PG8_WAIT_V(8); PG8_WAIT_L(0); PG8_BAR; PG8_MMA(0, 0, At, B0); PG8_MMA(0, 1, At, B1); PG8_BAR; PG8_SCHED;
;             PG8_LDA(At, 0, 1); PG8_STAGE(PG8_SB(0, 0), b2, voffB); PG8_STAGE(PG8_SB(0, 1), b2 + hstep, voffB); PG8_STAGE(PG8_SA(0, 0), a2, voffA);
;             PG8_WAIT_V(8); PG8_WAIT_L(0); PG8_BAR; PG8_MMA(1, 0, At, B0); PG8_MMA(1, 1, At, B1); PG8_BAR; PG8_SCHED;
;             PG8_LDB(B0, 1, 0); PG8_LDB(B1, 1, 1); PG8_SCHED; PG8_LDA(At, 1, 0); PG8_STAGE(PG8_SA(0, 1), a2 + hstep, voffA);
;             PG8_WAIT_V(8); PG8_WAIT_L(0); PG8_BAR; PG8_MMA(0, 0, At, B0); PG8_MMA(0, 1, At, B1); PG8_BAR; PG8_SCHED;
	s_setprio 0
	s_waitcnt lgkmcnt(0)
	v_mfma_f32_16x16x32_bf16 v[60:63], v[104:107], v[184:187], v[60:63]
	v_mfma_f32_16x16x32_bf16 v[56:59], v[128:131], v[184:187], v[56:59]
	v_mfma_f32_16x16x32_bf16 v[44:47], v[104:107], v[192:195], v[44:47]
	v_mfma_f32_16x16x32_bf16 v[40:43], v[128:131], v[192:195], v[40:43]
	v_mfma_f32_16x16x32_bf16 v[28:31], v[104:107], v[200:203], v[28:31]
	v_mfma_f32_16x16x32_bf16 v[24:27], v[128:131], v[200:203], v[24:27]
	v_mfma_f32_16x16x32_bf16 v[12:15], v[104:107], v[208:211], v[12:15]
	v_mfma_f32_16x16x32_bf16 v[8:11], v[128:131], v[208:211], v[8:11]
	v_mfma_f32_16x16x32_bf16 v[60:63], v[120:123], v[188:191], v[60:63]
	v_mfma_f32_16x16x32_bf16 v[56:59], v[132:135], v[188:191], v[56:59]
	v_mfma_f32_16x16x32_bf16 v[44:47], v[120:123], v[196:199], v[44:47]
	v_mfma_f32_16x16x32_bf16 v[40:43], v[132:135], v[196:199], v[40:43]
	v_mfma_f32_16x16x32_bf16 v[28:31], v[120:123], v[204:207], v[28:31]
	v_mfma_f32_16x16x32_bf16 v[24:27], v[132:135], v[204:207], v[24:27]
	v_mfma_f32_16x16x32_bf16 v[12:15], v[120:123], v[212:215], v[12:15]
	v_mfma_f32_16x16x32_bf16 v[8:11], v[132:135], v[212:215], v[8:11]
	s_setprio 1
	s_setprio 0
	v_mfma_f32_16x16x32_bf16 v[52:55], v[136:139], v[184:187], v[52:55]
	v_mfma_f32_16x16x32_bf16 v[48:51], v[152:155], v[184:187], v[48:51]
	v_mfma_f32_16x16x32_bf16 v[36:39], v[136:139], v[192:195], v[36:39]
	v_mfma_f32_16x16x32_bf16 v[32:35], v[152:155], v[192:195], v[32:35]
	v_mfma_f32_16x16x32_bf16 v[20:23], v[136:139], v[200:203], v[20:23]
	v_mfma_f32_16x16x32_bf16 v[16:19], v[152:155], v[200:203], v[16:19]
	v_mfma_f32_16x16x32_bf16 v[4:7], v[136:139], v[208:211], v[4:7]
	v_mfma_f32_16x16x32_bf16 v[0:3], v[152:155], v[208:211], v[0:3]
	v_mfma_f32_16x16x32_bf16 v[52:55], v[148:151], v[188:191], v[52:55]
	v_mfma_f32_16x16x32_bf16 v[48:51], v[180:183], v[188:191], v[48:51]
	v_mfma_f32_16x16x32_bf16 v[36:39], v[148:151], v[196:199], v[36:39]
	v_mfma_f32_16x16x32_bf16 v[32:35], v[180:183], v[196:199], v[32:35]
	v_mfma_f32_16x16x32_bf16 v[20:23], v[148:151], v[204:207], v[20:23]
	v_mfma_f32_16x16x32_bf16 v[16:19], v[180:183], v[204:207], v[16:19]
	v_mfma_f32_16x16x32_bf16 v[4:7], v[148:151], v[212:215], v[4:7]
	v_mfma_f32_16x16x32_bf16 v[0:3], v[180:183], v[212:215], v[0:3]
	s_setprio 1
	s_barrier
	s_add_i32 s34, 0, 0x18000
	s_add_i32 s35, 0, 0x1c000
	v_add_u32_e32 v132, s34, v169
	v_add_u32_e32 v180, s35, v169
	ds_read_b128 v[104:107], v132
	ds_read_b128 v[120:123], v132 offset:1024
	ds_read_b128 v[128:131], v132 offset:2048
	ds_read_b128 v[132:135], v132 offset:3072
	ds_read_b128 v[136:139], v180
	ds_read_b128 v[148:151], v180 offset:1024
	ds_read_b128 v[152:155], v180 offset:2048
	ds_read_b128 v[180:183], v180 offset:3072
	s_add_u32 s10, s16, 0xb0000
	s_addc_u32 s11, s17, 0
	s_mov_b32 m0, s54
	v_lshl_add_u64 v[224:225], s[10:11], 0, v[174:175]
	ds_read_b128 v[184:187], v239 offset:32768
	ds_read_b128 v[188:191], v239 offset:33792
	ds_read_b128 v[192:195], v239 offset:34816
	ds_read_b128 v[196:199], v239 offset:35840
	ds_read_b128 v[200:203], v239 offset:36864
	ds_read_b128 v[204:207], v239 offset:37888
	ds_read_b128 v[208:211], v239 offset:38912
	ds_read_b128 v[212:215], v239 offset:39936
	global_load_lds_dwordx4 v[224:225], off
	v_lshl_add_u64 v[224:225], s[10:11], 0, v[172:173]
	s_mov_b32 m0, s55
	s_nop 0
	global_load_lds_dwordx4 v[224:225], off
	s_waitcnt vmcnt(8)
	s_waitcnt lgkmcnt(0)
	s_barrier
	s_setprio 0
	s_waitcnt lgkmcnt(0)
	v_mfma_f32_16x16x32_bf16 v[144:147], v[104:107], v[184:187], v[144:147]
	v_mfma_f32_16x16x32_bf16 v[140:143], v[128:131], v[184:187], v[140:143]
	v_mfma_f32_16x16x32_bf16 v[112:115], v[104:107], v[192:195], v[112:115]
	v_mfma_f32_16x16x32_bf16 v[108:111], v[128:131], v[192:195], v[108:111]
	v_mfma_f32_16x16x32_bf16 v[92:95], v[104:107], v[200:203], v[92:95]
	v_mfma_f32_16x16x32_bf16 v[88:91], v[128:131], v[200:203], v[88:91]
	v_mfma_f32_16x16x32_bf16 v[76:79], v[104:107], v[208:211], v[76:79]
	v_mfma_f32_16x16x32_bf16 v[72:75], v[128:131], v[208:211], v[72:75]
	v_mfma_f32_16x16x32_bf16 v[144:147], v[120:123], v[188:191], v[144:147]
	v_mfma_f32_16x16x32_bf16 v[140:143], v[132:135], v[188:191], v[140:143]
	v_mfma_f32_16x16x32_bf16 v[112:115], v[120:123], v[196:199], v[112:115]
	v_mfma_f32_16x16x32_bf16 v[108:111], v[132:135], v[196:199], v[108:111]
	v_mfma_f32_16x16x32_bf16 v[92:95], v[120:123], v[204:207], v[92:95]
	v_mfma_f32_16x16x32_bf16 v[88:91], v[132:135], v[204:207], v[88:91]
	v_mfma_f32_16x16x32_bf16 v[76:79], v[120:123], v[212:215], v[76:79]
	v_mfma_f32_16x16x32_bf16 v[72:75], v[132:135], v[212:215], v[72:75]
	s_setprio 1
	s_setprio 0
	v_mfma_f32_16x16x32_bf16 v[124:127], v[136:139], v[184:187], v[124:127]
	v_mfma_f32_16x16x32_bf16 v[116:119], v[152:155], v[184:187], v[116:119]
	v_mfma_f32_16x16x32_bf16 v[100:103], v[136:139], v[192:195], v[100:103]
	v_mfma_f32_16x16x32_bf16 v[96:99], v[152:155], v[192:195], v[96:99]
	v_mfma_f32_16x16x32_bf16 v[84:87], v[136:139], v[200:203], v[84:87]
	v_mfma_f32_16x16x32_bf16 v[80:83], v[152:155], v[200:203], v[80:83]
	v_mfma_f32_16x16x32_bf16 v[68:71], v[136:139], v[208:211], v[68:71]
	v_mfma_f32_16x16x32_bf16 v[64:67], v[152:155], v[208:211], v[64:67]
	v_mfma_f32_16x16x32_bf16 v[124:127], v[148:151], v[188:191], v[124:127]
	v_mfma_f32_16x16x32_bf16 v[116:119], v[180:183], v[188:191], v[116:119]
	v_mfma_f32_16x16x32_bf16 v[100:103], v[148:151], v[196:199], v[100:103]
	v_mfma_f32_16x16x32_bf16 v[96:99], v[180:183], v[196:199], v[96:99]
	v_mfma_f32_16x16x32_bf16 v[84:87], v[148:151], v[204:207], v[84:87]
	v_mfma_f32_16x16x32_bf16 v[80:83], v[180:183], v[204:207], v[80:83]
	v_mfma_f32_16x16x32_bf16 v[68:71], v[148:151], v[212:215], v[68:71]
	v_mfma_f32_16x16x32_bf16 v[64:67], v[180:183], v[212:215], v[64:67]
	s_setprio 1
	s_barrier
; #define PG8_STAGE(bufoff, gbase, voff) do { _Pragma("unroll") for (int _i = 0; _i < 2; ++_i) \
;         __builtin_amdgcn_global_load_lds((const unsigned*)((const char*)(gbase) + (voff)[_i]), (PG8_LAS unsigned*)(lds + (bufoff) + ldsw + _i * 8192), 16, 0, 0); } while (0)
; #define PG8_LDA(dst, b, h) do { _Pragma("unroll") for (int m = 0; m < 4; ++m) _Pragma("unroll") for (int k = 0; k < 2; ++k) dst[m][k] = *(const PG8_LAS bf16x8*)(lds + PG8_SA(b, h) + aoff + m * 2048 + k * 1024); } while (0)
; #define PG8_MMA(ai, bj, At, Bt) do { __builtin_amdgcn_s_setprio(1); _Pragma("unroll") for (int m = 0; m < 4; ++m) _Pragma("unroll") for (int n = 0; n < 2; ++n) _Pragma("unroll") for (int k = 0; k < 2; ++k) \
;         acc[ai][bj][m][n] = __builtin_amdgcn_mfma_f32_16x16x32_bf16(Bt[n][k], At[m][k], acc[ai][bj][m][n], 0, 0, 0); __builtin_amdgcn_s_setprio(0); } while (0)
; #define PG8_WAIT_V(n) asm volatile("s_waitcnt vmcnt(" #n ")" ::: "memory")
; #define PG8_WAIT_L(n) asm volatile("s_waitcnt lgkmcnt(" #n ")" ::: "memory")
; #define PG8_BAR __builtin_amdgcn_s_barrier()
; #define PG8_SCHED __builtin_amdgcn_sched_barrier(0)
; template <class Epi, class Sched, bool ALIGN_EPI = false, bool SP2 = false>
; __device__ __forceinline__ void gemm_phase(PG8_LAS unsigned char* lds, const Gemm g, const Sched& S, const Epi& E) {
;     ...
;         for (int t = 0; t < nt; t += 2) {
;     ...
;             PG8_LDA(At, 1, 1); PG8_STAGE(PG8_SB(1, 0), b3, voffB); PG8_STAGE(PG8_SB(1, 1), b3 + hstep, voffB); PG8_STAGE(PG8_SA(1, 0), a3, voffA);
;             PG8_WAIT_V(8); PG8_WAIT_L(0); PG8_BAR; PG8_MMA(1, 0, At, B0); PG8_MMA(1, 1, At, B1); PG8_BAR; PG8_SCHED;
	s_add_i32 s10, s34, s20
	v_lshl_add_u64 v[216:217], v[216:217], 0, s[96:97]
	s_mov_b32 m0, s10
	ds_read_b128 v[184:187], v239 offset:49152
	ds_read_b128 v[188:191], v239 offset:50176
	ds_read_b128 v[192:195], v239 offset:51200
	ds_read_b128 v[196:199], v239 offset:52224
	ds_read_b128 v[200:203], v239 offset:53248
	ds_read_b128 v[204:207], v239 offset:54272
	ds_read_b128 v[208:211], v239 offset:55296
	ds_read_b128 v[212:215], v239 offset:56320
	global_load_lds_dwordx4 v[216:217], off
	s_add_i32 m0, s10, 0x2000
	s_add_u32 s10, s14, 0xb0080
	v_lshl_add_u64 v[216:217], v[218:219], 0, s[96:97]
	s_addc_u32 s11, s15, 0
	s_add_i32 s14, s35, s20
	global_load_lds_dwordx4 v[216:217], off
	v_lshl_add_u64 v[216:217], s[10:11], 0, v[156:157]
	s_mov_b32 m0, s14
	s_nop 0
	global_load_lds_dwordx4 v[216:217], off
	v_lshl_add_u64 v[216:217], s[10:11], 0, v[170:171]
	s_add_i32 m0, s14, 0x2000
	s_nop 0
	global_load_lds_dwordx4 v[216:217], off
	v_lshl_add_u64 v[216:217], v[220:221], 0, s[96:97]
	s_mov_b32 m0, s57
	s_nop 0
	global_load_lds_dwordx4 v[216:217], off
	v_lshl_add_u64 v[216:217], v[222:223], 0, s[96:97]
	s_mov_b32 m0, s58
	s_nop 0
	global_load_lds_dwordx4 v[216:217], off
	s_waitcnt vmcnt(8)
	s_waitcnt lgkmcnt(0)
	s_barrier
	s_setprio 0
	s_waitcnt lgkmcnt(0)
	v_mfma_f32_16x16x32_bf16 v[60:63], v[104:107], v[184:187], v[60:63]
	v_mfma_f32_16x16x32_bf16 v[56:59], v[128:131], v[184:187], v[56:59]
	v_mfma_f32_16x16x32_bf16 v[44:47], v[104:107], v[192:195], v[44:47]
	v_mfma_f32_16x16x32_bf16 v[40:43], v[128:131], v[192:195], v[40:43]
	v_mfma_f32_16x16x32_bf16 v[28:31], v[104:107], v[200:203], v[28:31]
	v_mfma_f32_16x16x32_bf16 v[24:27], v[128:131], v[200:203], v[24:27]
	v_mfma_f32_16x16x32_bf16 v[12:15], v[104:107], v[208:211], v[12:15]
	v_mfma_f32_16x16x32_bf16 v[8:11], v[128:131], v[208:211], v[8:11]
	v_mfma_f32_16x16x32_bf16 v[60:63], v[120:123], v[188:191], v[60:63]
	v_mfma_f32_16x16x32_bf16 v[56:59], v[132:135], v[188:191], v[56:59]
	v_mfma_f32_16x16x32_bf16 v[44:47], v[120:123], v[196:199], v[44:47]
	v_mfma_f32_16x16x32_bf16 v[40:43], v[132:135], v[196:199], v[40:43]
	v_mfma_f32_16x16x32_bf16 v[28:31], v[120:123], v[204:207], v[28:31]
	v_mfma_f32_16x16x32_bf16 v[24:27], v[132:135], v[204:207], v[24:27]
	v_mfma_f32_16x16x32_bf16 v[12:15], v[120:123], v[212:215], v[12:15]
	v_mfma_f32_16x16x32_bf16 v[8:11], v[132:135], v[212:215], v[8:11]
	s_setprio 1
	s_setprio 0
	v_mfma_f32_16x16x32_bf16 v[52:55], v[136:139], v[184:187], v[52:55]
	v_mfma_f32_16x16x32_bf16 v[48:51], v[152:155], v[184:187], v[48:51]
	v_mfma_f32_16x16x32_bf16 v[36:39], v[136:139], v[192:195], v[36:39]
	v_mfma_f32_16x16x32_bf16 v[32:35], v[152:155], v[192:195], v[32:35]
	v_mfma_f32_16x16x32_bf16 v[20:23], v[136:139], v[200:203], v[20:23]
	v_mfma_f32_16x16x32_bf16 v[16:19], v[152:155], v[200:203], v[16:19]
	v_mfma_f32_16x16x32_bf16 v[4:7], v[136:139], v[208:211], v[4:7]
	v_mfma_f32_16x16x32_bf16 v[0:3], v[152:155], v[208:211], v[0:3]
	v_mfma_f32_16x16x32_bf16 v[52:55], v[148:151], v[188:191], v[52:55]
	v_mfma_f32_16x16x32_bf16 v[48:51], v[180:183], v[188:191], v[48:51]
	v_mfma_f32_16x16x32_bf16 v[36:39], v[148:151], v[196:199], v[36:39]
	v_mfma_f32_16x16x32_bf16 v[32:35], v[180:183], v[196:199], v[32:35]
	v_mfma_f32_16x16x32_bf16 v[20:23], v[148:151], v[204:207], v[20:23]
	v_mfma_f32_16x16x32_bf16 v[16:19], v[180:183], v[204:207], v[16:19]
	v_mfma_f32_16x16x32_bf16 v[4:7], v[148:151], v[212:215], v[4:7]
	v_mfma_f32_16x16x32_bf16 v[0:3], v[180:183], v[212:215], v[0:3]
	s_setprio 1
	s_barrier
	s_add_i32 s31, s31, 2
	s_add_u32 s29, s29, 0x100
	s_addc_u32 s30, s30, 0
	s_cmp_gt_u32 s31, 41
	s_mov_b64 s[10:11], s[12:13]
	s_cbranch_scc0 .LBB0_264
	s_and_b64 vcc, exec, s[52:53]
	s_cbranch_vccz .LBB0_267
	s_barrier

; #define PG8_STAGE(bufoff, gbase, voff) do { _Pragma("unroll") for (int _i = 0; _i < 2; ++_i) \
;         __builtin_amdgcn_global_load_lds((const unsigned*)((const char*)(gbase) + (voff)[_i]), (PG8_LAS unsigned*)(lds + (bufoff) + ldsw + _i * 8192), 16, 0, 0); } while (0)
; #define PG8_LDA(dst, b, h) do { _Pragma("unroll") for (int m = 0; m < 4; ++m) _Pragma("unroll") for (int k = 0; k < 2; ++k) dst[m][k] = *(const PG8_LAS bf16x8*)(lds + PG8_SA(b, h) + aoff + m * 2048 + k * 1024); } while (0)
; #define PG8_LDB(dst, b, h) do { _Pragma("unroll") for (int n = 0; n < 2; ++n) _Pragma("unroll") for (int k = 0; k < 2; ++k) dst[n][k] = *(const PG8_LAS bf16x8*)(lds + PG8_SB(b, h) + boff + n * 2048 + k * 1024); } while (0)
; #define PG8_MMA(ai, bj, At, Bt) do { __builtin_amdgcn_s_setprio(1); _Pragma("unroll") for (int m = 0; m < 4; ++m) _Pragma("unroll") for (int n = 0; n < 2; ++n) _Pragma("unroll") for (int k = 0; k < 2; ++k) \
;         acc[ai][bj][m][n] = __builtin_amdgcn_mfma_f32_16x16x32_bf16(Bt[n][k], At[m][k], acc[ai][bj][m][n], 0, 0, 0); __builtin_amdgcn_s_setprio(0); } while (0)
; #define PG8_WAIT_V(n) asm volatile("s_waitcnt vmcnt(" #n ")" ::: "memory")
; #define PG8_WAIT_L(n) asm volatile("s_waitcnt lgkmcnt(" #n ")" ::: "memory")
; #define PG8_BAR __builtin_amdgcn_s_barrier()
; #define PG8_SCHED __builtin_amdgcn_sched_barrier(0)
; template <class Epi, class Sched, bool ALIGN_EPI = false, bool SP2 = false>
; __device__ __forceinline__ void gemm_phase(PG8_LAS unsigned char* lds, const Gemm g, const Sched& S, const Epi& E) {
;     ...
;             PG8_LDB(B0, 0, 0); PG8_LDB(B1, 0, 1); PG8_SCHED; PG8_LDA(At, 0, 0); PG8_STAGE(PG8_SA(1, 1), a1 + hstep, voffA);
;             PG8_WAIT_V(8); PG8_WAIT_L(0); PG8_BAR; PG8_MMA(0, 0, At, B0); PG8_MMA(0, 1, At, B1); PG8_BAR; PG8_SCHED;
;             PG8_LDA(At, 0, 1); PG8_STAGE(PG8_SB(0, 0), b2, voffB); PG8_STAGE(PG8_SB(0, 1), b2 + hstep, voffB); PG8_STAGE(PG8_SA(0, 0), a2, voffA);
.LBB0_356:
	s_add_u32 s8, s6, 0xfffc0080
	s_addc_u32 s9, s7, -1
	s_add_i32 s54, 0, 0x10000
	s_cmp_eq_u32 s47, 12
	s_cselect_b32 s11, s29, s9
	s_cselect_b32 s10, s30, s8
	s_cselect_b32 s9, s31, s45
	s_cselect_b32 s8, s34, s35
	s_add_i32 s56, 0, 0x14000
	v_add_u32_e32 v132, s54, v169
	v_add_u32_e32 v180, s56, v169
	ds_read_b128 v[104:107], v132
	ds_read_b128 v[116:119], v132 offset:1024
	ds_read_b128 v[128:131], v132 offset:2048
	ds_read_b128 v[132:135], v132 offset:3072
	ds_read_b128 v[136:139], v180
	ds_read_b128 v[140:143], v180 offset:1024
	ds_read_b128 v[144:147], v180 offset:2048
	ds_read_b128 v[180:183], v180 offset:3072
	v_lshl_add_u64 v[216:217], s[6:7], 0, v[176:177]
	s_add_i32 m0, s15, 0xc000
	ds_read_b128 v[184:187], v239
	ds_read_b128 v[188:191], v239 offset:1024
	ds_read_b128 v[192:195], v239 offset:2048
	ds_read_b128 v[196:199], v239 offset:3072
	ds_read_b128 v[200:203], v239 offset:4096
	ds_read_b128 v[204:207], v239 offset:5120
	ds_read_b128 v[208:211], v239 offset:6144
	ds_read_b128 v[212:215], v239 offset:7168
	global_load_lds_dwordx4 v[216:217], off
	v_lshl_add_u64 v[216:217], s[6:7], 0, v[178:179]
	s_add_i32 m0, s15, 0xe000
	s_nop 0
	global_load_lds_dwordx4 v[216:217], off
	s_waitcnt vmcnt(8)
	s_waitcnt lgkmcnt(0)
	s_barrier
	s_setprio 0
	s_waitcnt lgkmcnt(0)
	v_mfma_f32_16x16x32_bf16 v[152:155], v[104:107], v[184:187], v[152:155]
	v_mfma_f32_16x16x32_bf16 v[148:151], v[128:131], v[184:187], v[148:151]
	v_mfma_f32_16x16x32_bf16 v[112:115], v[104:107], v[192:195], v[112:115]
	v_mfma_f32_16x16x32_bf16 v[108:111], v[128:131], v[192:195], v[108:111]
	v_mfma_f32_16x16x32_bf16 v[92:95], v[104:107], v[200:203], v[92:95]
	v_mfma_f32_16x16x32_bf16 v[88:91], v[128:131], v[200:203], v[88:91]
	v_mfma_f32_16x16x32_bf16 v[76:79], v[104:107], v[208:211], v[76:79]
	v_mfma_f32_16x16x32_bf16 v[72:75], v[128:131], v[208:211], v[72:75]
	v_mfma_f32_16x16x32_bf16 v[152:155], v[116:119], v[188:191], v[152:155]
	v_mfma_f32_16x16x32_bf16 v[148:151], v[132:135], v[188:191], v[148:151]
	v_mfma_f32_16x16x32_bf16 v[112:115], v[116:119], v[196:199], v[112:115]
	v_mfma_f32_16x16x32_bf16 v[108:111], v[132:135], v[196:199], v[108:111]
	v_mfma_f32_16x16x32_bf16 v[92:95], v[116:119], v[204:207], v[92:95]
	v_mfma_f32_16x16x32_bf16 v[88:91], v[132:135], v[204:207], v[88:91]
	v_mfma_f32_16x16x32_bf16 v[76:79], v[116:119], v[212:215], v[76:79]
	v_mfma_f32_16x16x32_bf16 v[72:75], v[132:135], v[212:215], v[72:75]
	s_setprio 1
	s_setprio 0
	v_mfma_f32_16x16x32_bf16 v[124:127], v[136:139], v[184:187], v[124:127]
	v_mfma_f32_16x16x32_bf16 v[120:123], v[144:147], v[184:187], v[120:123]
	v_mfma_f32_16x16x32_bf16 v[100:103], v[136:139], v[192:195], v[100:103]
	v_mfma_f32_16x16x32_bf16 v[96:99], v[144:147], v[192:195], v[96:99]
	v_mfma_f32_16x16x32_bf16 v[84:87], v[136:139], v[200:203], v[84:87]
	v_mfma_f32_16x16x32_bf16 v[80:83], v[144:147], v[200:203], v[80:83]
	v_mfma_f32_16x16x32_bf16 v[68:71], v[136:139], v[208:211], v[68:71]
	v_mfma_f32_16x16x32_bf16 v[64:67], v[144:147], v[208:211], v[64:67]
	v_mfma_f32_16x16x32_bf16 v[124:127], v[140:143], v[188:191], v[124:127]
	v_mfma_f32_16x16x32_bf16 v[120:123], v[180:183], v[188:191], v[120:123]
	v_mfma_f32_16x16x32_bf16 v[100:103], v[140:143], v[196:199], v[100:103]
	v_mfma_f32_16x16x32_bf16 v[96:99], v[180:183], v[196:199], v[96:99]
	v_mfma_f32_16x16x32_bf16 v[84:87], v[140:143], v[204:207], v[84:87]
	v_mfma_f32_16x16x32_bf16 v[80:83], v[180:183], v[204:207], v[80:83]
	v_mfma_f32_16x16x32_bf16 v[68:71], v[140:143], v[212:215], v[68:71]
	v_mfma_f32_16x16x32_bf16 v[64:67], v[180:183], v[212:215], v[64:67]
	s_setprio 1
	s_barrier
	s_add_i32 s54, s54, s14
	v_lshl_add_u64 v[216:217], s[8:9], 0, v[156:157]
	s_mov_b32 m0, s54
	ds_read_b128 v[184:187], v239 offset:16384
	ds_read_b128 v[188:191], v239 offset:17408
	ds_read_b128 v[192:195], v239 offset:18432
	ds_read_b128 v[196:199], v239 offset:19456
	ds_read_b128 v[200:203], v239 offset:20480
	ds_read_b128 v[204:207], v239 offset:21504
	ds_read_b128 v[208:211], v239 offset:22528
	ds_read_b128 v[212:215], v239 offset:23552
	global_load_lds_dwordx4 v[216:217], off
	s_add_i32 m0, s54, 0x2000
	s_add_u32 s54, s8, 0x40000
	v_lshl_add_u64 v[218:219], s[8:9], 0, v[170:171]
	s_addc_u32 s55, s9, 0
	s_add_i32 s56, s56, s14
	global_load_lds_dwordx4 v[218:219], off
	v_lshl_add_u64 v[220:221], s[54:55], 0, v[156:157]
	s_mov_b32 m0, s56
	v_lshl_add_u64 v[222:223], s[10:11], 0, v[172:173]
	global_load_lds_dwordx4 v[220:221], off
	v_lshl_add_u64 v[220:221], s[54:55], 0, v[170:171]
	s_add_i32 m0, s56, 0x2000
	s_nop 0
	global_load_lds_dwordx4 v[220:221], off
	v_lshl_add_u64 v[220:221], s[10:11], 0, v[174:175]
	s_mov_b32 m0, s15
	s_nop 0
	global_load_lds_dwordx4 v[220:221], off
	s_mov_b32 m0, s16
	s_nop 0
	global_load_lds_dwordx4 v[222:223], off
	s_waitcnt vmcnt(8)
	s_waitcnt lgkmcnt(0)
	s_barrier
; #define PG8_STAGE(bufoff, gbase, voff) do { _Pragma("unroll") for (int _i = 0; _i < 2; ++_i) \
;         __builtin_amdgcn_global_load_lds((const unsigned*)((const char*)(gbase) + (voff)[_i]), (PG8_LAS unsigned*)(lds + (bufoff) + ldsw + _i * 8192), 16, 0, 0); } while (0)
; #define PG8_LDA(dst, b, h) do { _Pragma("unroll") for (int m = 0; m < 4; ++m) _Pragma("unroll") for (int k = 0; k < 2; ++k) dst[m][k] = *(const PG8_LAS bf16x8*)(lds + PG8_SA(b, h) + aoff + m * 2048 + k * 1024); } while (0)
; #define PG8_LDB(dst, b, h) do { _Pragma("unroll") for (int n = 0; n < 2; ++n) _Pragma("unroll") for (int k = 0; k < 2; ++k) dst[n][k] = *(const PG8_LAS bf16x8*)(lds + PG8_SB(b, h) + boff + n * 2048 + k * 1024); } while (0)
; #define PG8_MMA(ai, bj, At, Bt) do { __builtin_amdgcn_s_setprio(1); _Pragma("unroll") for (int m = 0; m < 4; ++m) _Pragma("unroll") for (int n = 0; n < 2; ++n) _Pragma("unroll") for (int k = 0; k < 2; ++k) \
;         acc[ai][bj][m][n] = __builtin_amdgcn_mfma_f32_16x16x32_bf16(Bt[n][k], At[m][k], acc[ai][bj][m][n], 0, 0, 0); __builtin_amdgcn_s_setprio(0); } while (0)
; #define PG8_WAIT_V(n) asm volatile("s_waitcnt vmcnt(" #n ")" ::: "memory")
; #define PG8_WAIT_L(n) asm volatile("s_waitcnt lgkmcnt(" #n ")" ::: "memory")
; #define PG8_BAR __builtin_amdgcn_s_barrier()
; #define PG8_SCHED __builtin_amdgcn_sched_barrier(0)
; template <class Epi, class Sched, bool ALIGN_EPI = false, bool SP2 = false>
; __device__ __forceinline__ void gemm_phase(PG8_LAS unsigned char* lds, const Gemm g, const Sched& S, const Epi& E) {
;     ...
;             PG8_WAIT_V(8); PG8_WAIT_L(0); PG8_BAR; PG8_MMA(1, 0, At, B0); PG8_MMA(1, 1, At, B1); PG8_BAR; PG8_SCHED;
;             PG8_LDB(B0, 1, 0); PG8_LDB(B1, 1, 1); PG8_SCHED; PG8_LDA(At, 1, 0); PG8_STAGE(PG8_SA(0, 1), a2 + hstep, voffA);
;             PG8_WAIT_V(8); PG8_WAIT_L(0); PG8_BAR; PG8_MMA(0, 0, At, B0); PG8_MMA(0, 1, At, B1); PG8_BAR; PG8_SCHED;
	s_setprio 0
	s_waitcnt lgkmcnt(0)
	v_mfma_f32_16x16x32_bf16 v[60:63], v[104:107], v[184:187], v[60:63]
	v_mfma_f32_16x16x32_bf16 v[56:59], v[128:131], v[184:187], v[56:59]
	v_mfma_f32_16x16x32_bf16 v[44:47], v[104:107], v[192:195], v[44:47]
	v_mfma_f32_16x16x32_bf16 v[40:43], v[128:131], v[192:195], v[40:43]
	v_mfma_f32_16x16x32_bf16 v[28:31], v[104:107], v[200:203], v[28:31]
	v_mfma_f32_16x16x32_bf16 v[24:27], v[128:131], v[200:203], v[24:27]
	v_mfma_f32_16x16x32_bf16 v[12:15], v[104:107], v[208:211], v[12:15]
	v_mfma_f32_16x16x32_bf16 v[8:11], v[128:131], v[208:211], v[8:11]
	v_mfma_f32_16x16x32_bf16 v[60:63], v[116:119], v[188:191], v[60:63]
	v_mfma_f32_16x16x32_bf16 v[56:59], v[132:135], v[188:191], v[56:59]
	v_mfma_f32_16x16x32_bf16 v[44:47], v[116:119], v[196:199], v[44:47]
	v_mfma_f32_16x16x32_bf16 v[40:43], v[132:135], v[196:199], v[40:43]
	v_mfma_f32_16x16x32_bf16 v[28:31], v[116:119], v[204:207], v[28:31]
	v_mfma_f32_16x16x32_bf16 v[24:27], v[132:135], v[204:207], v[24:27]
	v_mfma_f32_16x16x32_bf16 v[12:15], v[116:119], v[212:215], v[12:15]
	v_mfma_f32_16x16x32_bf16 v[8:11], v[132:135], v[212:215], v[8:11]
	s_setprio 1
	s_setprio 0
	v_mfma_f32_16x16x32_bf16 v[52:55], v[136:139], v[184:187], v[52:55]
	v_mfma_f32_16x16x32_bf16 v[48:51], v[144:147], v[184:187], v[48:51]
	v_mfma_f32_16x16x32_bf16 v[36:39], v[136:139], v[192:195], v[36:39]
	v_mfma_f32_16x16x32_bf16 v[32:35], v[144:147], v[192:195], v[32:35]
	v_mfma_f32_16x16x32_bf16 v[20:23], v[136:139], v[200:203], v[20:23]
	v_mfma_f32_16x16x32_bf16 v[16:19], v[144:147], v[200:203], v[16:19]
	v_mfma_f32_16x16x32_bf16 v[4:7], v[136:139], v[208:211], v[4:7]
	v_mfma_f32_16x16x32_bf16 v[0:3], v[144:147], v[208:211], v[0:3]
	v_mfma_f32_16x16x32_bf16 v[52:55], v[140:143], v[188:191], v[52:55]
	v_mfma_f32_16x16x32_bf16 v[48:51], v[180:183], v[188:191], v[48:51]
	v_mfma_f32_16x16x32_bf16 v[36:39], v[140:143], v[196:199], v[36:39]
	v_mfma_f32_16x16x32_bf16 v[32:35], v[180:183], v[196:199], v[32:35]
	v_mfma_f32_16x16x32_bf16 v[20:23], v[140:143], v[204:207], v[20:23]
	v_mfma_f32_16x16x32_bf16 v[16:19], v[180:183], v[204:207], v[16:19]
	v_mfma_f32_16x16x32_bf16 v[4:7], v[140:143], v[212:215], v[4:7]
	v_mfma_f32_16x16x32_bf16 v[0:3], v[180:183], v[212:215], v[0:3]
	s_setprio 1
	s_barrier
	s_add_i32 s54, 0, 0x18000
	s_add_i32 s55, 0, 0x1c000
	v_add_u32_e32 v132, s54, v169
	v_add_u32_e32 v180, s55, v169
	ds_read_b128 v[104:107], v132
	ds_read_b128 v[116:119], v132 offset:1024
	ds_read_b128 v[128:131], v132 offset:2048
	ds_read_b128 v[132:135], v132 offset:3072
	ds_read_b128 v[136:139], v180
	ds_read_b128 v[140:143], v180 offset:1024
	ds_read_b128 v[144:147], v180 offset:2048
	ds_read_b128 v[180:183], v180 offset:3072
	s_add_u32 s10, s10, 0x40000
	s_addc_u32 s11, s11, 0
	s_mov_b32 m0, s17
	v_lshl_add_u64 v[224:225], s[10:11], 0, v[174:175]
	ds_read_b128 v[184:187], v239 offset:32768
	ds_read_b128 v[188:191], v239 offset:33792
	ds_read_b128 v[192:195], v239 offset:34816
	ds_read_b128 v[196:199], v239 offset:35840
	ds_read_b128 v[200:203], v239 offset:36864
	ds_read_b128 v[204:207], v239 offset:37888
	ds_read_b128 v[208:211], v239 offset:38912
	ds_read_b128 v[212:215], v239 offset:39936
	global_load_lds_dwordx4 v[224:225], off
	v_lshl_add_u64 v[224:225], s[10:11], 0, v[172:173]
	s_mov_b32 m0, s18
	s_nop 0
	global_load_lds_dwordx4 v[224:225], off
	s_waitcnt vmcnt(8)
	s_waitcnt lgkmcnt(0)
	s_barrier
	s_setprio 0
	s_waitcnt lgkmcnt(0)
	v_mfma_f32_16x16x32_bf16 v[152:155], v[104:107], v[184:187], v[152:155]
	v_mfma_f32_16x16x32_bf16 v[148:151], v[128:131], v[184:187], v[148:151]
	v_mfma_f32_16x16x32_bf16 v[112:115], v[104:107], v[192:195], v[112:115]
	v_mfma_f32_16x16x32_bf16 v[108:111], v[128:131], v[192:195], v[108:111]
	v_mfma_f32_16x16x32_bf16 v[92:95], v[104:107], v[200:203], v[92:95]
	v_mfma_f32_16x16x32_bf16 v[88:91], v[128:131], v[200:203], v[88:91]
	v_mfma_f32_16x16x32_bf16 v[76:79], v[104:107], v[208:211], v[76:79]
	v_mfma_f32_16x16x32_bf16 v[72:75], v[128:131], v[208:211], v[72:75]
	v_mfma_f32_16x16x32_bf16 v[152:155], v[116:119], v[188:191], v[152:155]
	v_mfma_f32_16x16x32_bf16 v[148:151], v[132:135], v[188:191], v[148:151]
	v_mfma_f32_16x16x32_bf16 v[112:115], v[116:119], v[196:199], v[112:115]
	v_mfma_f32_16x16x32_bf16 v[108:111], v[132:135], v[196:199], v[108:111]
	v_mfma_f32_16x16x32_bf16 v[92:95], v[116:119], v[204:207], v[92:95]
	v_mfma_f32_16x16x32_bf16 v[88:91], v[132:135], v[204:207], v[88:91]
	v_mfma_f32_16x16x32_bf16 v[76:79], v[116:119], v[212:215], v[76:79]
	v_mfma_f32_16x16x32_bf16 v[72:75], v[132:135], v[212:215], v[72:75]
	s_setprio 1
	s_setprio 0
	v_mfma_f32_16x16x32_bf16 v[124:127], v[136:139], v[184:187], v[124:127]
	v_mfma_f32_16x16x32_bf16 v[120:123], v[144:147], v[184:187], v[120:123]
	v_mfma_f32_16x16x32_bf16 v[100:103], v[136:139], v[192:195], v[100:103]
	v_mfma_f32_16x16x32_bf16 v[96:99], v[144:147], v[192:195], v[96:99]
	v_mfma_f32_16x16x32_bf16 v[84:87], v[136:139], v[200:203], v[84:87]
	v_mfma_f32_16x16x32_bf16 v[80:83], v[144:147], v[200:203], v[80:83]
	v_mfma_f32_16x16x32_bf16 v[68:71], v[136:139], v[208:211], v[68:71]
	v_mfma_f32_16x16x32_bf16 v[64:67], v[144:147], v[208:211], v[64:67]
	v_mfma_f32_16x16x32_bf16 v[124:127], v[140:143], v[188:191], v[124:127]
	v_mfma_f32_16x16x32_bf16 v[120:123], v[180:183], v[188:191], v[120:123]
	v_mfma_f32_16x16x32_bf16 v[100:103], v[140:143], v[196:199], v[100:103]
	v_mfma_f32_16x16x32_bf16 v[96:99], v[180:183], v[196:199], v[96:99]
	v_mfma_f32_16x16x32_bf16 v[84:87], v[140:143], v[204:207], v[84:87]
	v_mfma_f32_16x16x32_bf16 v[80:83], v[180:183], v[204:207], v[80:83]
	v_mfma_f32_16x16x32_bf16 v[68:71], v[140:143], v[212:215], v[68:71]
	v_mfma_f32_16x16x32_bf16 v[64:67], v[180:183], v[212:215], v[64:67]
	s_setprio 1
	s_barrier
; #define PG8_STAGE(bufoff, gbase, voff) do { _Pragma("unroll") for (int _i = 0; _i < 2; ++_i) \
;         __builtin_amdgcn_global_load_lds((const unsigned*)((const char*)(gbase) + (voff)[_i]), (PG8_LAS unsigned*)(lds + (bufoff) + ldsw + _i * 8192), 16, 0, 0); } while (0)
; #define PG8_LDA(dst, b, h) do { _Pragma("unroll") for (int m = 0; m < 4; ++m) _Pragma("unroll") for (int k = 0; k < 2; ++k) dst[m][k] = *(const PG8_LAS bf16x8*)(lds + PG8_SA(b, h) + aoff + m * 2048 + k * 1024); } while (0)
; #define PG8_MMA(ai, bj, At, Bt) do { __builtin_amdgcn_s_setprio(1); _Pragma("unroll") for (int m = 0; m < 4; ++m) _Pragma("unroll") for (int n = 0; n < 2; ++n) _Pragma("unroll") for (int k = 0; k < 2; ++k) \
;         acc[ai][bj][m][n] = __builtin_amdgcn_mfma_f32_16x16x32_bf16(Bt[n][k], At[m][k], acc[ai][bj][m][n], 0, 0, 0); __builtin_amdgcn_s_setprio(0); } while (0)
; #define PG8_WAIT_V(n) asm volatile("s_waitcnt vmcnt(" #n ")" ::: "memory")
; #define PG8_WAIT_L(n) asm volatile("s_waitcnt lgkmcnt(" #n ")" ::: "memory")
; #define PG8_BAR __builtin_amdgcn_s_barrier()
; #define PG8_SCHED __builtin_amdgcn_sched_barrier(0)
; template <class Epi, class Sched, bool ALIGN_EPI = false, bool SP2 = false>
; __device__ __forceinline__ void gemm_phase(PG8_LAS unsigned char* lds, const Gemm g, const Sched& S, const Epi& E) {
;     ...
;         for (int t = 0; t < nt; t += 2) {
;     ...
;             PG8_LDA(At, 1, 1); PG8_STAGE(PG8_SB(1, 0), b3, voffB); PG8_STAGE(PG8_SB(1, 1), b3 + hstep, voffB); PG8_STAGE(PG8_SA(1, 0), a3, voffA);
;             PG8_WAIT_V(8); PG8_WAIT_L(0); PG8_BAR; PG8_MMA(1, 0, At, B0); PG8_MMA(1, 1, At, B1); PG8_BAR; PG8_SCHED;
	s_add_i32 s10, s54, s14
	v_lshl_add_u64 v[216:217], v[216:217], 0, s[96:97]
	s_mov_b32 m0, s10
	ds_read_b128 v[184:187], v239 offset:49152
	ds_read_b128 v[188:191], v239 offset:50176
	ds_read_b128 v[192:195], v239 offset:51200
	ds_read_b128 v[196:199], v239 offset:52224
	ds_read_b128 v[200:203], v239 offset:53248
	ds_read_b128 v[204:207], v239 offset:54272
	ds_read_b128 v[208:211], v239 offset:55296
	ds_read_b128 v[212:215], v239 offset:56320
	global_load_lds_dwordx4 v[216:217], off
	s_add_i32 m0, s10, 0x2000
	s_add_u32 s8, s8, 0x40080
	v_lshl_add_u64 v[216:217], v[218:219], 0, s[96:97]
	s_addc_u32 s9, s9, 0
	s_add_i32 s10, s55, s14
	global_load_lds_dwordx4 v[216:217], off
	v_lshl_add_u64 v[216:217], s[8:9], 0, v[156:157]
	s_mov_b32 m0, s10
	s_nop 0
	global_load_lds_dwordx4 v[216:217], off
	v_lshl_add_u64 v[216:217], s[8:9], 0, v[170:171]
	s_add_i32 m0, s10, 0x2000
	s_nop 0
	global_load_lds_dwordx4 v[216:217], off
	v_lshl_add_u64 v[216:217], v[220:221], 0, s[96:97]
	s_mov_b32 m0, s19
	s_nop 0
	global_load_lds_dwordx4 v[216:217], off
	v_lshl_add_u64 v[216:217], v[222:223], 0, s[96:97]
	s_mov_b32 m0, s20
	s_nop 0
	global_load_lds_dwordx4 v[216:217], off
	s_waitcnt vmcnt(8)
	s_waitcnt lgkmcnt(0)
	s_barrier
	s_setprio 0
	s_waitcnt lgkmcnt(0)
	v_mfma_f32_16x16x32_bf16 v[60:63], v[104:107], v[184:187], v[60:63]
	v_mfma_f32_16x16x32_bf16 v[56:59], v[128:131], v[184:187], v[56:59]
	v_mfma_f32_16x16x32_bf16 v[44:47], v[104:107], v[192:195], v[44:47]
	v_mfma_f32_16x16x32_bf16 v[40:43], v[128:131], v[192:195], v[40:43]
	v_mfma_f32_16x16x32_bf16 v[28:31], v[104:107], v[200:203], v[28:31]
	v_mfma_f32_16x16x32_bf16 v[24:27], v[128:131], v[200:203], v[24:27]
	v_mfma_f32_16x16x32_bf16 v[12:15], v[104:107], v[208:211], v[12:15]
	v_mfma_f32_16x16x32_bf16 v[8:11], v[128:131], v[208:211], v[8:11]
	v_mfma_f32_16x16x32_bf16 v[60:63], v[116:119], v[188:191], v[60:63]
	v_mfma_f32_16x16x32_bf16 v[56:59], v[132:135], v[188:191], v[56:59]
	v_mfma_f32_16x16x32_bf16 v[44:47], v[116:119], v[196:199], v[44:47]
	v_mfma_f32_16x16x32_bf16 v[40:43], v[132:135], v[196:199], v[40:43]
	v_mfma_f32_16x16x32_bf16 v[28:31], v[116:119], v[204:207], v[28:31]
	v_mfma_f32_16x16x32_bf16 v[24:27], v[132:135], v[204:207], v[24:27]
	v_mfma_f32_16x16x32_bf16 v[12:15], v[116:119], v[212:215], v[12:15]
	v_mfma_f32_16x16x32_bf16 v[8:11], v[132:135], v[212:215], v[8:11]
	s_setprio 1
	s_setprio 0
	v_mfma_f32_16x16x32_bf16 v[52:55], v[136:139], v[184:187], v[52:55]
	v_mfma_f32_16x16x32_bf16 v[48:51], v[144:147], v[184:187], v[48:51]
	v_mfma_f32_16x16x32_bf16 v[36:39], v[136:139], v[192:195], v[36:39]
	v_mfma_f32_16x16x32_bf16 v[32:35], v[144:147], v[192:195], v[32:35]
	v_mfma_f32_16x16x32_bf16 v[20:23], v[136:139], v[200:203], v[20:23]
	v_mfma_f32_16x16x32_bf16 v[16:19], v[144:147], v[200:203], v[16:19]
	v_mfma_f32_16x16x32_bf16 v[4:7], v[136:139], v[208:211], v[4:7]
	v_mfma_f32_16x16x32_bf16 v[0:3], v[144:147], v[208:211], v[0:3]
	v_mfma_f32_16x16x32_bf16 v[52:55], v[140:143], v[188:191], v[52:55]
	v_mfma_f32_16x16x32_bf16 v[48:51], v[180:183], v[188:191], v[48:51]
	v_mfma_f32_16x16x32_bf16 v[36:39], v[140:143], v[196:199], v[36:39]
	v_mfma_f32_16x16x32_bf16 v[32:35], v[180:183], v[196:199], v[32:35]
	v_mfma_f32_16x16x32_bf16 v[20:23], v[140:143], v[204:207], v[20:23]
	v_mfma_f32_16x16x32_bf16 v[16:19], v[180:183], v[204:207], v[16:19]
	v_mfma_f32_16x16x32_bf16 v[4:7], v[140:143], v[212:215], v[4:7]
	v_mfma_f32_16x16x32_bf16 v[0:3], v[180:183], v[212:215], v[0:3]
	s_setprio 1
	s_barrier
	s_add_i32 s47, s47, 2
	s_add_u32 s6, s6, 0x100
	s_addc_u32 s7, s7, 0
	s_add_u32 s35, s35, 0x100
	s_addc_u32 s45, s45, 0
	s_cmp_gt_u32 s47, 13
	s_cbranch_scc0 .LBB0_356
	s_and_b64 vcc, exec, s[42:43]
	s_cbranch_vccz .LBB0_359
	s_barrier

; #define PG8_STAGE(bufoff, gbase, voff) do { _Pragma("unroll") for (int _i = 0; _i < 2; ++_i) \
;         __builtin_amdgcn_global_load_lds((const unsigned*)((const char*)(gbase) + (voff)[_i]), (PG8_LAS unsigned*)(lds + (bufoff) + ldsw + _i * 8192), 16, 0, 0); } while (0)
; #define PG8_LDA(dst, b, h) do { _Pragma("unroll") for (int m = 0; m < 4; ++m) _Pragma("unroll") for (int k = 0; k < 2; ++k) dst[m][k] = *(const PG8_LAS bf16x8*)(lds + PG8_SA(b, h) + aoff + m * 2048 + k * 1024); } while (0)
; #define PG8_LDB(dst, b, h) do { _Pragma("unroll") for (int n = 0; n < 2; ++n) _Pragma("unroll") for (int k = 0; k < 2; ++k) dst[n][k] = *(const PG8_LAS bf16x8*)(lds + PG8_SB(b, h) + boff + n * 2048 + k * 1024); } while (0)
; #define PG8_MMA(ai, bj, At, Bt) do { __builtin_amdgcn_s_setprio(1); _Pragma("unroll") for (int m = 0; m < 4; ++m) _Pragma("unroll") for (int n = 0; n < 2; ++n) _Pragma("unroll") for (int k = 0; k < 2; ++k) \
;         acc[ai][bj][m][n] = __builtin_amdgcn_mfma_f32_16x16x32_bf16(Bt[n][k], At[m][k], acc[ai][bj][m][n], 0, 0, 0); __builtin_amdgcn_s_setprio(0); } while (0)
; #define PG8_WAIT_V(n) asm volatile("s_waitcnt vmcnt(" #n ")" ::: "memory")
; #define PG8_WAIT_L(n) asm volatile("s_waitcnt lgkmcnt(" #n ")" ::: "memory")
; #define PG8_BAR __builtin_amdgcn_s_barrier()
; #define PG8_SCHED __builtin_amdgcn_sched_barrier(0)
; template <class Epi, class Sched, bool ALIGN_EPI = false, bool SP2 = false>
; __device__ __forceinline__ void gemm_phase(PG8_LAS unsigned char* lds, const Gemm g, const Sched& S, const Epi& E) {
;     ...
;             PG8_LDB(B0, 0, 0); PG8_LDB(B1, 0, 1); PG8_SCHED; PG8_LDA(At, 0, 0); PG8_STAGE(PG8_SA(1, 1), a1 + hstep, voffA);
;             PG8_WAIT_V(8); PG8_WAIT_L(0); PG8_BAR; PG8_MMA(0, 0, At, B0); PG8_MMA(0, 1, At, B1); PG8_BAR; PG8_SCHED;
;             PG8_LDA(At, 0, 1); PG8_STAGE(PG8_SB(0, 0), b2, voffB); PG8_STAGE(PG8_SB(0, 1), b2 + hstep, voffB); PG8_STAGE(PG8_SA(0, 0), a2, voffA);
.LBB0_399:
	s_add_u32 s12, s10, 0xfffc0080
	s_addc_u32 s13, s11, -1
	s_add_i32 s51, 0, 0x10000
	s_cmp_eq_u32 s50, 12
	s_cselect_b32 s15, s41, s13
	s_cselect_b32 s14, s46, s12
	v_add_u32_e32 v146, s51, v149
	s_cselect_b32 s13, s9, s49
	s_cselect_b32 s12, s47, s48
	s_add_i32 s54, 0, 0x14000
	ds_read_b128 v[138:141], v146
	ds_read_b128 v[142:145], v146 offset:1024
	ds_read_b128 v[168:171], v146 offset:2048
	ds_read_b128 v[172:175], v146 offset:3072
	v_add_u32_e32 v146, s54, v149
	ds_read_b128 v[176:179], v146
	ds_read_b128 v[180:183], v146 offset:1024
	ds_read_b128 v[184:187], v146 offset:2048
	ds_read_b128 v[188:191], v146 offset:3072
	v_lshl_add_u64 v[146:147], s[10:11], 0, v[134:135]
	s_add_i32 m0, s25, 0xc000
	ds_read_b128 v[192:195], v152
	ds_read_b128 v[196:199], v152 offset:1024
	ds_read_b128 v[200:203], v152 offset:2048
	ds_read_b128 v[204:207], v152 offset:3072
	ds_read_b128 v[208:211], v152 offset:4096
	ds_read_b128 v[212:215], v152 offset:5120
	ds_read_b128 v[216:219], v152 offset:6144
	ds_read_b128 v[220:223], v152 offset:7168
	global_load_lds_dwordx4 v[146:147], off
	v_lshl_add_u64 v[146:147], s[10:11], 0, v[136:137]
	s_add_i32 m0, s25, 0xe000
	s_nop 0
	global_load_lds_dwordx4 v[146:147], off
	s_waitcnt vmcnt(8)
	s_waitcnt lgkmcnt(0)
	s_barrier
	s_setprio 0
	s_waitcnt lgkmcnt(0)
	v_mfma_f32_16x16x32_bf16 v[124:127], v[138:141], v[192:195], v[124:127]
	v_mfma_f32_16x16x32_bf16 v[120:123], v[168:171], v[192:195], v[120:123]
	v_mfma_f32_16x16x32_bf16 v[108:111], v[138:141], v[200:203], v[108:111]
	v_mfma_f32_16x16x32_bf16 v[104:107], v[168:171], v[200:203], v[104:107]
	v_mfma_f32_16x16x32_bf16 v[92:95], v[138:141], v[208:211], v[92:95]
	v_mfma_f32_16x16x32_bf16 v[88:91], v[168:171], v[208:211], v[88:91]
	v_mfma_f32_16x16x32_bf16 v[76:79], v[138:141], v[216:219], v[76:79]
	v_mfma_f32_16x16x32_bf16 v[72:75], v[168:171], v[216:219], v[72:75]
	v_mfma_f32_16x16x32_bf16 v[124:127], v[142:145], v[196:199], v[124:127]
	v_mfma_f32_16x16x32_bf16 v[120:123], v[172:175], v[196:199], v[120:123]
	v_mfma_f32_16x16x32_bf16 v[108:111], v[142:145], v[204:207], v[108:111]
	v_mfma_f32_16x16x32_bf16 v[104:107], v[172:175], v[204:207], v[104:107]
	v_mfma_f32_16x16x32_bf16 v[92:95], v[142:145], v[212:215], v[92:95]
	v_mfma_f32_16x16x32_bf16 v[88:91], v[172:175], v[212:215], v[88:91]
	v_mfma_f32_16x16x32_bf16 v[76:79], v[142:145], v[220:223], v[76:79]
	v_mfma_f32_16x16x32_bf16 v[72:75], v[172:175], v[220:223], v[72:75]
	s_setprio 1
	s_setprio 0
	v_mfma_f32_16x16x32_bf16 v[116:119], v[176:179], v[192:195], v[116:119]
	v_mfma_f32_16x16x32_bf16 v[112:115], v[184:187], v[192:195], v[112:115]
	v_mfma_f32_16x16x32_bf16 v[100:103], v[176:179], v[200:203], v[100:103]
	v_mfma_f32_16x16x32_bf16 v[96:99], v[184:187], v[200:203], v[96:99]
	v_mfma_f32_16x16x32_bf16 v[84:87], v[176:179], v[208:211], v[84:87]
	v_mfma_f32_16x16x32_bf16 v[80:83], v[184:187], v[208:211], v[80:83]
	v_mfma_f32_16x16x32_bf16 v[68:71], v[176:179], v[216:219], v[68:71]
	v_mfma_f32_16x16x32_bf16 v[64:67], v[184:187], v[216:219], v[64:67]
	v_mfma_f32_16x16x32_bf16 v[116:119], v[180:183], v[196:199], v[116:119]
	v_mfma_f32_16x16x32_bf16 v[112:115], v[188:191], v[196:199], v[112:115]
	v_mfma_f32_16x16x32_bf16 v[100:103], v[180:183], v[204:207], v[100:103]
	v_mfma_f32_16x16x32_bf16 v[96:99], v[188:191], v[204:207], v[96:99]
	v_mfma_f32_16x16x32_bf16 v[84:87], v[180:183], v[212:215], v[84:87]
	v_mfma_f32_16x16x32_bf16 v[80:83], v[188:191], v[212:215], v[80:83]
	v_mfma_f32_16x16x32_bf16 v[68:71], v[180:183], v[220:223], v[68:71]
	v_mfma_f32_16x16x32_bf16 v[64:67], v[188:191], v[220:223], v[64:67]
	s_setprio 1
	s_barrier
	s_add_i32 s51, s51, s21
	v_lshl_add_u64 v[146:147], s[12:13], 0, v[156:157]
	s_mov_b32 m0, s51
	ds_read_b128 v[192:195], v152 offset:16384
	ds_read_b128 v[196:199], v152 offset:17408
	ds_read_b128 v[200:203], v152 offset:18432
	ds_read_b128 v[204:207], v152 offset:19456
	ds_read_b128 v[208:211], v152 offset:20480
	ds_read_b128 v[212:215], v152 offset:21504
	ds_read_b128 v[216:219], v152 offset:22528
	ds_read_b128 v[220:223], v152 offset:23552
	global_load_lds_dwordx4 v[146:147], off
	s_add_i32 m0, s51, 0x2000
	s_add_u32 s52, s12, 0x40000
	v_lshl_add_u64 v[154:155], s[12:13], 0, v[128:129]
	s_addc_u32 s53, s13, 0
	s_add_i32 s51, s54, s21
	global_load_lds_dwordx4 v[154:155], off
	v_lshl_add_u64 v[224:225], s[52:53], 0, v[156:157]
	s_mov_b32 m0, s51
	v_lshl_add_u64 v[226:227], s[14:15], 0, v[130:131]
	global_load_lds_dwordx4 v[224:225], off
	v_lshl_add_u64 v[224:225], s[52:53], 0, v[128:129]
	s_add_i32 m0, s51, 0x2000
	s_nop 0
	global_load_lds_dwordx4 v[224:225], off
	v_lshl_add_u64 v[224:225], s[14:15], 0, v[132:133]
	s_mov_b32 m0, s25
	s_nop 0
	global_load_lds_dwordx4 v[224:225], off
	s_mov_b32 m0, s26
	s_nop 0
	global_load_lds_dwordx4 v[226:227], off
	s_waitcnt vmcnt(8)
	s_waitcnt lgkmcnt(0)
	s_barrier
; #define PG8_STAGE(bufoff, gbase, voff) do { _Pragma("unroll") for (int _i = 0; _i < 2; ++_i) \
;         __builtin_amdgcn_global_load_lds((const unsigned*)((const char*)(gbase) + (voff)[_i]), (PG8_LAS unsigned*)(lds + (bufoff) + ldsw + _i * 8192), 16, 0, 0); } while (0)
; #define PG8_LDA(dst, b, h) do { _Pragma("unroll") for (int m = 0; m < 4; ++m) _Pragma("unroll") for (int k = 0; k < 2; ++k) dst[m][k] = *(const PG8_LAS bf16x8*)(lds + PG8_SA(b, h) + aoff + m * 2048 + k * 1024); } while (0)
; #define PG8_LDB(dst, b, h) do { _Pragma("unroll") for (int n = 0; n < 2; ++n) _Pragma("unroll") for (int k = 0; k < 2; ++k) dst[n][k] = *(const PG8_LAS bf16x8*)(lds + PG8_SB(b, h) + boff + n * 2048 + k * 1024); } while (0)
; #define PG8_MMA(ai, bj, At, Bt) do { __builtin_amdgcn_s_setprio(1); _Pragma("unroll") for (int m = 0; m < 4; ++m) _Pragma("unroll") for (int n = 0; n < 2; ++n) _Pragma("unroll") for (int k = 0; k < 2; ++k) \
;         acc[ai][bj][m][n] = __builtin_amdgcn_mfma_f32_16x16x32_bf16(Bt[n][k], At[m][k], acc[ai][bj][m][n], 0, 0, 0); __builtin_amdgcn_s_setprio(0); } while (0)
; #define PG8_WAIT_V(n) asm volatile("s_waitcnt vmcnt(" #n ")" ::: "memory")
; #define PG8_WAIT_L(n) asm volatile("s_waitcnt lgkmcnt(" #n ")" ::: "memory")
; #define PG8_BAR __builtin_amdgcn_s_barrier()
; #define PG8_SCHED __builtin_amdgcn_sched_barrier(0)
; template <class Epi, class Sched, bool ALIGN_EPI = false, bool SP2 = false>
; __device__ __forceinline__ void gemm_phase(PG8_LAS unsigned char* lds, const Gemm g, const Sched& S, const Epi& E) {
;     ...
;             PG8_WAIT_V(8); PG8_WAIT_L(0); PG8_BAR; PG8_MMA(1, 0, At, B0); PG8_MMA(1, 1, At, B1); PG8_BAR; PG8_SCHED;
;             PG8_LDB(B0, 1, 0); PG8_LDB(B1, 1, 1); PG8_SCHED; PG8_LDA(At, 1, 0); PG8_STAGE(PG8_SA(0, 1), a2 + hstep, voffA);
;             PG8_WAIT_V(8); PG8_WAIT_L(0); PG8_BAR; PG8_MMA(0, 0, At, B0); PG8_MMA(0, 1, At, B1); PG8_BAR; PG8_SCHED;
	s_setprio 0
	s_waitcnt lgkmcnt(0)
	v_mfma_f32_16x16x32_bf16 v[60:63], v[138:141], v[192:195], v[60:63]
	v_mfma_f32_16x16x32_bf16 v[56:59], v[168:171], v[192:195], v[56:59]
	v_mfma_f32_16x16x32_bf16 v[44:47], v[138:141], v[200:203], v[44:47]
	v_mfma_f32_16x16x32_bf16 v[40:43], v[168:171], v[200:203], v[40:43]
	v_mfma_f32_16x16x32_bf16 v[28:31], v[138:141], v[208:211], v[28:31]
	v_mfma_f32_16x16x32_bf16 v[24:27], v[168:171], v[208:211], v[24:27]
	v_mfma_f32_16x16x32_bf16 v[12:15], v[138:141], v[216:219], v[12:15]
	v_mfma_f32_16x16x32_bf16 v[8:11], v[168:171], v[216:219], v[8:11]
	v_mfma_f32_16x16x32_bf16 v[60:63], v[142:145], v[196:199], v[60:63]
	v_mfma_f32_16x16x32_bf16 v[56:59], v[172:175], v[196:199], v[56:59]
	v_mfma_f32_16x16x32_bf16 v[44:47], v[142:145], v[204:207], v[44:47]
	v_mfma_f32_16x16x32_bf16 v[40:43], v[172:175], v[204:207], v[40:43]
	v_mfma_f32_16x16x32_bf16 v[28:31], v[142:145], v[212:215], v[28:31]
	v_mfma_f32_16x16x32_bf16 v[24:27], v[172:175], v[212:215], v[24:27]
	v_mfma_f32_16x16x32_bf16 v[12:15], v[142:145], v[220:223], v[12:15]
	v_mfma_f32_16x16x32_bf16 v[8:11], v[172:175], v[220:223], v[8:11]
	s_setprio 1
	s_setprio 0
	v_mfma_f32_16x16x32_bf16 v[52:55], v[176:179], v[192:195], v[52:55]
	v_mfma_f32_16x16x32_bf16 v[48:51], v[184:187], v[192:195], v[48:51]
	v_mfma_f32_16x16x32_bf16 v[36:39], v[176:179], v[200:203], v[36:39]
	v_mfma_f32_16x16x32_bf16 v[32:35], v[184:187], v[200:203], v[32:35]
	v_mfma_f32_16x16x32_bf16 v[20:23], v[176:179], v[208:211], v[20:23]
	v_mfma_f32_16x16x32_bf16 v[16:19], v[184:187], v[208:211], v[16:19]
	v_mfma_f32_16x16x32_bf16 v[4:7], v[176:179], v[216:219], v[4:7]
	v_mfma_f32_16x16x32_bf16 v[0:3], v[184:187], v[216:219], v[0:3]
	v_mfma_f32_16x16x32_bf16 v[52:55], v[180:183], v[196:199], v[52:55]
	v_mfma_f32_16x16x32_bf16 v[48:51], v[188:191], v[196:199], v[48:51]
	v_mfma_f32_16x16x32_bf16 v[36:39], v[180:183], v[204:207], v[36:39]
	v_mfma_f32_16x16x32_bf16 v[32:35], v[188:191], v[204:207], v[32:35]
	v_mfma_f32_16x16x32_bf16 v[20:23], v[180:183], v[212:215], v[20:23]
	v_mfma_f32_16x16x32_bf16 v[16:19], v[188:191], v[212:215], v[16:19]
	v_mfma_f32_16x16x32_bf16 v[4:7], v[180:183], v[220:223], v[4:7]
	v_mfma_f32_16x16x32_bf16 v[0:3], v[188:191], v[220:223], v[0:3]
	s_setprio 1
	s_barrier
	s_add_i32 s51, 0, 0x18000
	v_add_u32_e32 v153, s51, v149
	s_add_i32 s52, 0, 0x1c000
	ds_read_b128 v[138:141], v153
	ds_read_b128 v[142:145], v153 offset:1024
	ds_read_b128 v[168:171], v153 offset:2048
	ds_read_b128 v[172:175], v153 offset:3072
	v_add_u32_e32 v153, s52, v149
	ds_read_b128 v[176:179], v153
	ds_read_b128 v[180:183], v153 offset:1024
	ds_read_b128 v[184:187], v153 offset:2048
	ds_read_b128 v[188:191], v153 offset:3072
	s_add_u32 s14, s14, 0x40000
	s_addc_u32 s15, s15, 0
	s_mov_b32 m0, s27
	v_lshl_add_u64 v[228:229], s[14:15], 0, v[132:133]
	ds_read_b128 v[192:195], v152 offset:32768
	ds_read_b128 v[196:199], v152 offset:33792
	ds_read_b128 v[200:203], v152 offset:34816
	ds_read_b128 v[204:207], v152 offset:35840
	ds_read_b128 v[208:211], v152 offset:36864
	ds_read_b128 v[212:215], v152 offset:37888
	ds_read_b128 v[216:219], v152 offset:38912
	ds_read_b128 v[220:223], v152 offset:39936
	global_load_lds_dwordx4 v[228:229], off
	v_lshl_add_u64 v[228:229], s[14:15], 0, v[130:131]
	s_mov_b32 m0, s28
	s_nop 0
	global_load_lds_dwordx4 v[228:229], off
	s_waitcnt vmcnt(8)
	s_waitcnt lgkmcnt(0)
	s_barrier
	s_setprio 0
	s_waitcnt lgkmcnt(0)
	v_mfma_f32_16x16x32_bf16 v[124:127], v[138:141], v[192:195], v[124:127]
	v_mfma_f32_16x16x32_bf16 v[120:123], v[168:171], v[192:195], v[120:123]
	v_mfma_f32_16x16x32_bf16 v[108:111], v[138:141], v[200:203], v[108:111]
	v_mfma_f32_16x16x32_bf16 v[104:107], v[168:171], v[200:203], v[104:107]
	v_mfma_f32_16x16x32_bf16 v[92:95], v[138:141], v[208:211], v[92:95]
	v_mfma_f32_16x16x32_bf16 v[88:91], v[168:171], v[208:211], v[88:91]
	v_mfma_f32_16x16x32_bf16 v[76:79], v[138:141], v[216:219], v[76:79]
	v_mfma_f32_16x16x32_bf16 v[72:75], v[168:171], v[216:219], v[72:75]
	v_mfma_f32_16x16x32_bf16 v[124:127], v[142:145], v[196:199], v[124:127]
	v_mfma_f32_16x16x32_bf16 v[120:123], v[172:175], v[196:199], v[120:123]
	v_mfma_f32_16x16x32_bf16 v[108:111], v[142:145], v[204:207], v[108:111]
	v_mfma_f32_16x16x32_bf16 v[104:107], v[172:175], v[204:207], v[104:107]
	v_mfma_f32_16x16x32_bf16 v[92:95], v[142:145], v[212:215], v[92:95]
	v_mfma_f32_16x16x32_bf16 v[88:91], v[172:175], v[212:215], v[88:91]
	v_mfma_f32_16x16x32_bf16 v[76:79], v[142:145], v[220:223], v[76:79]
	v_mfma_f32_16x16x32_bf16 v[72:75], v[172:175], v[220:223], v[72:75]
	s_setprio 1
	s_setprio 0
	v_mfma_f32_16x16x32_bf16 v[116:119], v[176:179], v[192:195], v[116:119]
	v_mfma_f32_16x16x32_bf16 v[112:115], v[184:187], v[192:195], v[112:115]
	v_mfma_f32_16x16x32_bf16 v[100:103], v[176:179], v[200:203], v[100:103]
	v_mfma_f32_16x16x32_bf16 v[96:99], v[184:187], v[200:203], v[96:99]
	v_mfma_f32_16x16x32_bf16 v[84:87], v[176:179], v[208:211], v[84:87]
	v_mfma_f32_16x16x32_bf16 v[80:83], v[184:187], v[208:211], v[80:83]
	v_mfma_f32_16x16x32_bf16 v[68:71], v[176:179], v[216:219], v[68:71]
	v_mfma_f32_16x16x32_bf16 v[64:67], v[184:187], v[216:219], v[64:67]
	v_mfma_f32_16x16x32_bf16 v[116:119], v[180:183], v[196:199], v[116:119]
	v_mfma_f32_16x16x32_bf16 v[112:115], v[188:191], v[196:199], v[112:115]
	v_mfma_f32_16x16x32_bf16 v[100:103], v[180:183], v[204:207], v[100:103]
	v_mfma_f32_16x16x32_bf16 v[96:99], v[188:191], v[204:207], v[96:99]
	v_mfma_f32_16x16x32_bf16 v[84:87], v[180:183], v[212:215], v[84:87]
	v_mfma_f32_16x16x32_bf16 v[80:83], v[188:191], v[212:215], v[80:83]
	v_mfma_f32_16x16x32_bf16 v[68:71], v[180:183], v[220:223], v[68:71]
	v_mfma_f32_16x16x32_bf16 v[64:67], v[188:191], v[220:223], v[64:67]
	s_setprio 1
	s_barrier
; #define PG8_STAGE(bufoff, gbase, voff) do { _Pragma("unroll") for (int _i = 0; _i < 2; ++_i) \
;         __builtin_amdgcn_global_load_lds((const unsigned*)((const char*)(gbase) + (voff)[_i]), (PG8_LAS unsigned*)(lds + (bufoff) + ldsw + _i * 8192), 16, 0, 0); } while (0)
; #define PG8_LDA(dst, b, h) do { _Pragma("unroll") for (int m = 0; m < 4; ++m) _Pragma("unroll") for (int k = 0; k < 2; ++k) dst[m][k] = *(const PG8_LAS bf16x8*)(lds + PG8_SA(b, h) + aoff + m * 2048 + k * 1024); } while (0)
; #define PG8_MMA(ai, bj, At, Bt) do { __builtin_amdgcn_s_setprio(1); _Pragma("unroll") for (int m = 0; m < 4; ++m) _Pragma("unroll") for (int n = 0; n < 2; ++n) _Pragma("unroll") for (int k = 0; k < 2; ++k) \
;         acc[ai][bj][m][n] = __builtin_amdgcn_mfma_f32_16x16x32_bf16(Bt[n][k], At[m][k], acc[ai][bj][m][n], 0, 0, 0); __builtin_amdgcn_s_setprio(0); } while (0)
; #define PG8_WAIT_V(n) asm volatile("s_waitcnt vmcnt(" #n ")" ::: "memory")
; #define PG8_WAIT_L(n) asm volatile("s_waitcnt lgkmcnt(" #n ")" ::: "memory")
; #define PG8_BAR __builtin_amdgcn_s_barrier()
; #define PG8_SCHED __builtin_amdgcn_sched_barrier(0)
; template <class Epi, class Sched, bool ALIGN_EPI = false, bool SP2 = false>
; __device__ __forceinline__ void gemm_phase(PG8_LAS unsigned char* lds, const Gemm g, const Sched& S, const Epi& E) {
;     ...
;         for (int t = 0; t < nt; t += 2) {
;     ...
;             PG8_LDA(At, 1, 1); PG8_STAGE(PG8_SB(1, 0), b3, voffB); PG8_STAGE(PG8_SB(1, 1), b3 + hstep, voffB); PG8_STAGE(PG8_SA(1, 0), a3, voffA);
;             PG8_WAIT_V(8); PG8_WAIT_L(0); PG8_BAR; PG8_MMA(1, 0, At, B0); PG8_MMA(1, 1, At, B1); PG8_BAR; PG8_SCHED;
	s_add_i32 s14, s51, s21
	v_lshl_add_u64 v[146:147], v[146:147], 0, s[96:97]
	s_mov_b32 m0, s14
	ds_read_b128 v[192:195], v152 offset:49152
	ds_read_b128 v[196:199], v152 offset:50176
	ds_read_b128 v[200:203], v152 offset:51200
	ds_read_b128 v[204:207], v152 offset:52224
	ds_read_b128 v[208:211], v152 offset:53248
	ds_read_b128 v[212:215], v152 offset:54272
	ds_read_b128 v[216:219], v152 offset:55296
	ds_read_b128 v[220:223], v152 offset:56320
	global_load_lds_dwordx4 v[146:147], off
	s_add_i32 m0, s14, 0x2000
	s_add_u32 s12, s12, 0x40080
	v_lshl_add_u64 v[146:147], v[154:155], 0, s[96:97]
	s_addc_u32 s13, s13, 0
	s_add_i32 s14, s52, s21
	global_load_lds_dwordx4 v[146:147], off
	v_lshl_add_u64 v[146:147], s[12:13], 0, v[156:157]
	s_mov_b32 m0, s14
	s_nop 0
	global_load_lds_dwordx4 v[146:147], off
	v_lshl_add_u64 v[146:147], s[12:13], 0, v[128:129]
	s_add_i32 m0, s14, 0x2000
	s_nop 0
	global_load_lds_dwordx4 v[146:147], off
	v_lshl_add_u64 v[146:147], v[224:225], 0, s[96:97]
	s_mov_b32 m0, s29
	s_nop 0
	global_load_lds_dwordx4 v[146:147], off
	v_lshl_add_u64 v[146:147], v[226:227], 0, s[96:97]
	s_mov_b32 m0, s30
	s_nop 0
	global_load_lds_dwordx4 v[146:147], off
	s_waitcnt vmcnt(8)
	s_waitcnt lgkmcnt(0)
	s_barrier
	s_setprio 0
	s_waitcnt lgkmcnt(0)
	v_mfma_f32_16x16x32_bf16 v[60:63], v[138:141], v[192:195], v[60:63]
	v_mfma_f32_16x16x32_bf16 v[56:59], v[168:171], v[192:195], v[56:59]
	v_mfma_f32_16x16x32_bf16 v[44:47], v[138:141], v[200:203], v[44:47]
	v_mfma_f32_16x16x32_bf16 v[40:43], v[168:171], v[200:203], v[40:43]
	v_mfma_f32_16x16x32_bf16 v[28:31], v[138:141], v[208:211], v[28:31]
	v_mfma_f32_16x16x32_bf16 v[24:27], v[168:171], v[208:211], v[24:27]
	v_mfma_f32_16x16x32_bf16 v[12:15], v[138:141], v[216:219], v[12:15]
	v_mfma_f32_16x16x32_bf16 v[8:11], v[168:171], v[216:219], v[8:11]
	v_mfma_f32_16x16x32_bf16 v[60:63], v[142:145], v[196:199], v[60:63]
	v_mfma_f32_16x16x32_bf16 v[56:59], v[172:175], v[196:199], v[56:59]
	v_mfma_f32_16x16x32_bf16 v[44:47], v[142:145], v[204:207], v[44:47]
	v_mfma_f32_16x16x32_bf16 v[40:43], v[172:175], v[204:207], v[40:43]
	v_mfma_f32_16x16x32_bf16 v[28:31], v[142:145], v[212:215], v[28:31]
	v_mfma_f32_16x16x32_bf16 v[24:27], v[172:175], v[212:215], v[24:27]
	v_mfma_f32_16x16x32_bf16 v[12:15], v[142:145], v[220:223], v[12:15]
	v_mfma_f32_16x16x32_bf16 v[8:11], v[172:175], v[220:223], v[8:11]
	s_setprio 1
	s_setprio 0
	v_mfma_f32_16x16x32_bf16 v[52:55], v[176:179], v[192:195], v[52:55]
	v_mfma_f32_16x16x32_bf16 v[48:51], v[184:187], v[192:195], v[48:51]
	v_mfma_f32_16x16x32_bf16 v[36:39], v[176:179], v[200:203], v[36:39]
	v_mfma_f32_16x16x32_bf16 v[32:35], v[184:187], v[200:203], v[32:35]
	v_mfma_f32_16x16x32_bf16 v[20:23], v[176:179], v[208:211], v[20:23]
	v_mfma_f32_16x16x32_bf16 v[16:19], v[184:187], v[208:211], v[16:19]
	v_mfma_f32_16x16x32_bf16 v[4:7], v[176:179], v[216:219], v[4:7]
	v_mfma_f32_16x16x32_bf16 v[0:3], v[184:187], v[216:219], v[0:3]
	v_mfma_f32_16x16x32_bf16 v[52:55], v[180:183], v[196:199], v[52:55]
	v_mfma_f32_16x16x32_bf16 v[48:51], v[188:191], v[196:199], v[48:51]
	v_mfma_f32_16x16x32_bf16 v[36:39], v[180:183], v[204:207], v[36:39]
	v_mfma_f32_16x16x32_bf16 v[32:35], v[188:191], v[204:207], v[32:35]
	v_mfma_f32_16x16x32_bf16 v[20:23], v[180:183], v[212:215], v[20:23]
	v_mfma_f32_16x16x32_bf16 v[16:19], v[188:191], v[212:215], v[16:19]
	v_mfma_f32_16x16x32_bf16 v[4:7], v[180:183], v[220:223], v[4:7]
	v_mfma_f32_16x16x32_bf16 v[0:3], v[188:191], v[220:223], v[0:3]
	s_setprio 1
	s_barrier
	s_add_i32 s50, s50, 2
	s_add_u32 s10, s10, 0x100
	s_addc_u32 s11, s11, 0
	s_add_u32 s48, s48, 0x100
	s_addc_u32 s49, s49, 0
	s_cmp_gt_u32 s50, 13
	s_cbranch_scc0 .LBB0_399
	s_and_b64 vcc, exec, s[6:7]
	s_cbranch_vccz .LBB0_402
	s_barrier
